# ConvGelu epilogue: 64 divergent saveexec/branch select ladders replaced by v_cmp masks + 3 v_cndmask each (on top of norm rewrite + K-loop barrier handoff)
# baseline (speedup 1.0000x reference)
; __device__ __forceinline__ unsigned cvt_pk_bf16(float lo, float hi) { unsigned r; asm volatile("v_cvt_pk_bf16_f32 %0, %1, %2" : "=v"(r) : "v"(lo), "v"(hi)); return r; }
; __device__ __forceinline__ float gelu_tanh_f(float x) { const float y = -2.3022081983651455f * (x + 0.044715f * x * x * x); return x * __builtin_amdgcn_rcpf(1.f + __builtin_amdgcn_exp2f(y)); }
;     __device__ __forceinline__ void operator()(const f32x4 (&acc)[2][2][4][2], const Unit& u, int wr, int wc, int fr, int fq) const {
;     ...
;                 for (int q = 0; q < 4; ++q) {
;                     unsigned g1 = (unsigned)__shfl_up((int)pk[q], 1, 16), g2 = (unsigned)__shfl_up((int)pk[q], 2, 16);
;                     if (fr == 0) { g1 = l15[q]; g2 = l14[q]; } else if (fr == 1) { g2 = l15[q]; }
;                     const unsigned n14 = (unsigned)__shfl((int)pk[q], 14, 16), n15 = (unsigned)__shfl((int)pk[q], 15, 16);
;                     l14[q] = n14; l15[q] = n15;
;                     const int n = q >> 1, j = (q & 1) * 2, e = 2 * q;
;                     const float x0 = bb[e] + w0[e] * __uint_as_float(g2 << 16) + w1[e] * __uint_as_float(g1 << 16) + w2[e] * acc[ai][0][m][n][j];
;                     const float x1 = bb[e + 1] + w0[e + 1] * __uint_as_float(g2 & 0xffff0000u) + w1[e + 1] * __uint_as_float(g1 & 0xffff0000u) + w2[e + 1] * acc[ai][0][m][n][j + 1];
;                     hv[e] = gelu_tanh_f(x0) * acc[ai][1][m][n][j]; hv[e + 1] = gelu_tanh_f(x1) * acc[ai][1][m][n][j + 1];
;                 }
;                 const bool first2 = (slab == 0 && m == 0 && fr < 2);
;                 if (!first2) { u32x4 w; w.x = cvt_pk_bf16(hv[0], hv[1]); w.y = cvt_pk_bf16(hv[2], hv[3]); w.z = cvt_pk_bf16(hv[4], hv[5]); w.w = cvt_pk_bf16(hv[6], hv[7]);
;                     *(u32x4*)(H + (size_t)row * ldh + f0) = w; }
.LBB0_1195:
	v_add_u32_e32 v182, -1, v199
	v_and_b32_e32 v183, 0x70, v199
	v_cmp_lt_i32_e32 vcc, v182, v183
	v_cvt_pk_bf16_f32 v204, v104, v105
	v_cvt_pk_bf16_f32 v211, v106, v107
	v_cvt_pk_bf16_f32 v208, v100, v101
	v_cvt_pk_bf16_f32 v187, v102, v103
	s_nop 1
	v_cndmask_b32_e32 v182, v182, v199, vcc
	v_lshlrev_b32_e32 v200, 2, v182
	v_add_u32_e32 v182, -2, v199
	v_cmp_lt_i32_e32 vcc, v182, v183
	s_nop 1
	v_cndmask_b32_e32 v182, v182, v199, vcc
	v_lshlrev_b32_e32 v201, 2, v182
	ds_bpermute_b32 v182, v200, v204
	ds_bpermute_b32 v183, v201, v204
	v_cmp_lt_i32_e32 vcc, 0, v188
	v_cmp_eq_u32_e64 s[98:99], 0, v188
	v_cmp_eq_u32_e64 s[100:101], 1, v188
	s_waitcnt lgkmcnt(0)
	s_nop 1
	v_cndmask_b32_e64 v183, v183, v203, s[100:101]
	v_cndmask_b32_e64 v183, v183, v186, s[98:99]
	v_cndmask_b32_e64 v182, v182, v203, s[98:99]
	v_lshlrev_b32_e32 v186, 2, v199
	v_and_b32_e32 v212, 0x1c0, v186
	v_or_b32_e32 v203, 60, v186
	ds_bpermute_b32 v209, v212, v204 offset:56
	ds_bpermute_b32 v205, v203, v204
	ds_bpermute_b32 v186, v200, v211
	ds_bpermute_b32 v213, v201, v211
	v_or_b32_e32 v204, 56, v212
	v_cmp_lt_i32_e32 vcc, 0, v188
	v_cmp_eq_u32_e64 s[98:99], 0, v188
	v_cmp_eq_u32_e64 s[100:101], 1, v188
	s_waitcnt lgkmcnt(0)
	s_nop 1
	v_cndmask_b32_e64 v213, v213, v210, s[100:101]
	v_cndmask_b32_e64 v213, v213, v206, s[98:99]
	v_cndmask_b32_e64 v186, v186, v210, s[98:99]
	ds_bpermute_b32 v210, v204, v211
	ds_bpermute_b32 v206, v203, v211
	ds_bpermute_b32 v216, v200, v208
	ds_bpermute_b32 v217, v201, v208
	v_cmp_lt_i32_e32 vcc, 0, v188
	v_cmp_eq_u32_e64 s[98:99], 0, v188
	v_cmp_eq_u32_e64 s[100:101], 1, v188
	s_waitcnt lgkmcnt(0)
	s_nop 1
	v_cndmask_b32_e64 v217, v217, v207, s[100:101]
	v_cndmask_b32_e64 v217, v217, v202, s[98:99]
	v_cndmask_b32_e64 v216, v216, v207, s[98:99]
	ds_bpermute_b32 v211, v204, v208
	ds_bpermute_b32 v207, v203, v208
	ds_bpermute_b32 v214, v200, v187
	ds_bpermute_b32 v215, v201, v187
	v_cmp_lt_i32_e32 vcc, 0, v188
	v_cmp_eq_u32_e64 s[98:99], 0, v188
	v_cmp_eq_u32_e64 s[100:101], 1, v188
	s_waitcnt lgkmcnt(0)
	s_nop 1
	v_cndmask_b32_e64 v215, v215, v185, s[100:101]
	v_cndmask_b32_e64 v215, v215, v184, s[98:99]
	v_cndmask_b32_e64 v214, v214, v185, s[98:99]
	ds_bpermute_b32 v212, v204, v187
	ds_bpermute_b32 v208, v203, v187
	s_mul_i32 s57, s62, 0x40800
	s_mul_hi_i32 s55, s62, 0x40800
	s_add_u32 s64, s80, s57
	s_addc_u32 s65, s81, s55
	v_lshl_add_u32 v202, s62, 8, v189
	s_and_saveexec_b64 s[62:63], s[24:25]
	s_xor_b64 s[62:63], exec, s[62:63]
	s_cbranch_execz .LBB0_1221
	s_waitcnt lgkmcnt(0)
	v_lshlrev_b32_e32 v184, 16, v217
	s_waitcnt vmcnt(0)
	v_fma_f32 v184, v56, v184, v52
	v_lshlrev_b32_e32 v185, 16, v216
	v_fmac_f32_e32 v184, v48, v185
	v_fmac_f32_e32 v184, v100, v44
	v_mul_f32_e32 v187, 0x3d372713, v184
	v_mul_f32_e32 v187, v184, v187
	v_and_b32_e32 v185, 0xffff0000, v217
	v_fma_f32 v187, v184, v187, v184
	v_fma_f32 v185, v57, v185, v53
	v_mul_f32_e32 v187, 0xc0135761, v187
	v_and_b32_e32 v216, 0xffff0000, v216
	v_exp_f32_e32 v187, v187
	v_fmac_f32_e32 v185, v49, v216
	v_fmac_f32_e32 v185, v101, v45
	v_mul_f32_e32 v216, 0x3d372713, v185
	v_mul_f32_e32 v216, v185, v216
	v_add_f32_e32 v187, 1.0, v187
	v_fma_f32 v216, v185, v216, v185
	v_rcp_f32_e32 v187, v187
	v_mul_f32_e32 v216, 0xc0135761, v216
	v_exp_f32_e32 v216, v216
	v_lshlrev_b32_e32 v217, 16, v186
	v_mul_f32_e32 v184, v184, v187
	v_mul_f32_e32 v187, v88, v184
	v_add_f32_e32 v184, 1.0, v216
	v_lshlrev_b32_e32 v216, 16, v213
	v_fma_f32 v216, v78, v216, v62
	v_and_b32_e32 v213, 0xffff0000, v213
	v_fmac_f32_e32 v216, v70, v217
	v_fma_f32 v213, v79, v213, v63
	v_and_b32_e32 v186, 0xffff0000, v186
	v_fmac_f32_e32 v216, v106, v74
	v_fmac_f32_e32 v213, v71, v186
	v_fmac_f32_e32 v213, v107, v75
	v_mul_f32_e32 v186, 0x3d372713, v216
	v_mul_f32_e32 v186, v216, v186
	v_mul_f32_e32 v217, 0x3d372713, v213
	v_fma_f32 v186, v216, v186, v216
	v_mul_f32_e32 v217, v213, v217
	v_mul_f32_e32 v186, 0xc0135761, v186
	v_fma_f32 v217, v213, v217, v213
	v_rcp_f32_e32 v184, v184
	v_exp_f32_e32 v186, v186
	v_mul_f32_e32 v217, 0xc0135761, v217
	v_exp_f32_e32 v217, v217
	v_mul_f32_e32 v184, v185, v184
	v_add_f32_e32 v185, 1.0, v186
	v_rcp_f32_e32 v185, v185
	v_add_f32_e32 v186, 1.0, v217
	v_rcp_f32_e32 v186, v186
	v_mul_f32_e32 v217, v89, v184
	v_mul_f32_e32 v184, v216, v185
	v_lshlrev_b32_e32 v185, 16, v183
	v_mul_f32_e32 v216, v94, v184
	v_mul_f32_e32 v184, v213, v186
	v_fma_f32 v185, v76, v185, v60
	v_lshlrev_b32_e32 v186, 16, v182
	v_fmac_f32_e32 v185, v68, v186
	v_fmac_f32_e32 v185, v104, v72
	v_and_b32_e32 v183, 0xffff0000, v183
	v_fma_f32 v186, v77, v183, v61
	v_mul_f32_e32 v183, 0x3d372713, v185
	v_mul_f32_e32 v183, v185, v183
	v_fma_f32 v183, v185, v183, v185
	v_mul_f32_e32 v183, 0xc0135761, v183
	v_exp_f32_e32 v183, v183
	v_and_b32_e32 v182, 0xffff0000, v182
	v_fmac_f32_e32 v186, v69, v182
	v_fmac_f32_e32 v186, v105, v73
	v_add_f32_e32 v182, 1.0, v183
	v_mul_f32_e32 v183, 0x3d372713, v186
	v_mul_f32_e32 v183, v186, v183
	v_fma_f32 v183, v186, v183, v186
	v_rcp_f32_e32 v182, v182
	v_mul_f32_e32 v183, 0xc0135761, v183
	v_exp_f32_e32 v183, v183
	v_mul_f32_e32 v213, v95, v184
	v_mul_f32_e32 v182, v185, v182
	v_mul_f32_e32 v218, v92, v182
	v_add_f32_e32 v182, 1.0, v183
	v_rcp_f32_e32 v219, v182
	v_and_b32_e32 v182, 0xffff0000, v215
	v_fma_f32 v220, v59, v182, v55
	v_and_b32_e32 v183, 0xffff0000, v214
	v_mov_b32_e32 v184, v103
	v_mov_b32_e32 v185, v51
	v_mov_b32_e32 v182, v47
	v_pk_mul_f32 v[182:183], v[184:185], v[182:183]
	v_mov_b32_e32 v184, v102
	v_add_f32_e32 v183, v220, v183
	v_add_f32_e32 v220, v182, v183
	v_mul_f32_e32 v182, 0x3d372713, v220
	v_mul_f32_e32 v182, v220, v182
	v_fma_f32 v182, v220, v182, v220
	v_mul_f32_e32 v182, 0xc0135761, v182
	v_exp_f32_e32 v221, v182
	v_lshlrev_b32_e32 v182, 16, v215
	v_fma_f32 v215, v58, v182, v54
	v_lshlrev_b32_e32 v183, 16, v214
	v_mov_b32_e32 v185, v50
	v_mov_b32_e32 v182, v46
	v_pk_mul_f32 v[182:183], v[184:185], v[182:183]
	v_add_f32_e32 v185, 1.0, v221
	v_add_f32_e32 v183, v215, v183
	v_add_f32_e32 v182, v182, v183
	v_mul_f32_e32 v183, 0x3d372713, v182
	v_mul_f32_e32 v183, v182, v183
	v_fma_f32 v183, v182, v183, v182
	v_mul_f32_e32 v183, 0xc0135761, v183
	v_exp_f32_e32 v183, v183
	v_rcp_f32_e32 v185, v185
	v_mul_f32_e32 v184, v186, v219
	v_mul_f32_e32 v184, v93, v184
	v_add_f32_e32 v183, 1.0, v183
	v_rcp_f32_e32 v183, v183
	v_mul_f32_e32 v185, v220, v185
	v_mul_f32_e32 v185, v91, v185
	v_mul_f32_e32 v182, v182, v183
	v_mul_f32_e32 v186, v90, v182
	v_cvt_pk_bf16_f32 v182, v218, v184
	v_cvt_pk_bf16_f32 v183, v216, v213
	v_cvt_pk_bf16_f32 v184, v187, v217
	v_cvt_pk_bf16_f32 v185, v186, v185
	v_mov_b64_e32 v[186:187], s[14:15]
	v_mad_i64_i32 v[186:187], s[66:67], v202, s91, v[186:187]
	v_lshl_add_u64 v[186:187], v[180:181], 1, v[186:187]
	global_store_dwordx4 v[186:187], v[182:185], off

; __device__ __forceinline__ unsigned cvt_pk_bf16(float lo, float hi) { unsigned r; asm volatile("v_cvt_pk_bf16_f32 %0, %1, %2" : "=v"(r) : "v"(lo), "v"(hi)); return r; }
; __device__ __forceinline__ float gelu_tanh_f(float x) { const float y = -2.3022081983651455f * (x + 0.044715f * x * x * x); return x * __builtin_amdgcn_rcpf(1.f + __builtin_amdgcn_exp2f(y)); }
;     __device__ __forceinline__ void operator()(const f32x4 (&acc)[2][2][4][2], const Unit& u, int wr, int wc, int fr, int fq) const {
;     ...
;                 for (int q = 0; q < 4; ++q) {
;                     unsigned g1 = (unsigned)__shfl_up((int)pk[q], 1, 16), g2 = (unsigned)__shfl_up((int)pk[q], 2, 16);
;                     if (fr == 0) { g1 = l15[q]; g2 = l14[q]; } else if (fr == 1) { g2 = l15[q]; }
;                     const unsigned n14 = (unsigned)__shfl((int)pk[q], 14, 16), n15 = (unsigned)__shfl((int)pk[q], 15, 16);
;                     l14[q] = n14; l15[q] = n15;
;                     const int n = q >> 1, j = (q & 1) * 2, e = 2 * q;
;                     const float x0 = bb[e] + w0[e] * __uint_as_float(g2 << 16) + w1[e] * __uint_as_float(g1 << 16) + w2[e] * acc[ai][0][m][n][j];
;                     const float x1 = bb[e + 1] + w0[e + 1] * __uint_as_float(g2 & 0xffff0000u) + w1[e + 1] * __uint_as_float(g1 & 0xffff0000u) + w2[e + 1] * acc[ai][0][m][n][j + 1];
;                     hv[e] = gelu_tanh_f(x0) * acc[ai][1][m][n][j]; hv[e + 1] = gelu_tanh_f(x1) * acc[ai][1][m][n][j + 1];
;                 }
;                 const bool first2 = (slab == 0 && m == 0 && fr < 2);
;                 if (!first2) { u32x4 w; w.x = cvt_pk_bf16(hv[0], hv[1]); w.y = cvt_pk_bf16(hv[2], hv[3]); w.z = cvt_pk_bf16(hv[4], hv[5]); w.w = cvt_pk_bf16(hv[6], hv[7]);
;                     *(u32x4*)(H + (size_t)row * ldh + f0) = w; }
.LBB0_1223:
	s_or_b64 exec, exec, s[62:63]
	v_cvt_pk_bf16_f32 v216, v156, v157
	ds_bpermute_b32 v214, v200, v216
	ds_bpermute_b32 v215, v201, v216
	v_cmp_lt_i32_e32 vcc, 0, v188
	v_cvt_pk_bf16_f32 v219, v158, v159
	v_cvt_pk_bf16_f32 v218, v148, v149
	v_cvt_pk_bf16_f32 v213, v150, v151
	v_cmp_eq_u32_e64 s[98:99], 0, v188
	v_cmp_eq_u32_e64 s[100:101], 1, v188
	s_waitcnt lgkmcnt(0)
	s_nop 1
	v_cndmask_b32_e64 v215, v215, v205, s[100:101]
	v_cndmask_b32_e64 v215, v215, v209, s[98:99]
	v_cndmask_b32_e64 v214, v214, v205, s[98:99]
	ds_bpermute_b32 v209, v204, v216
	ds_bpermute_b32 v205, v203, v216
	ds_bpermute_b32 v216, v200, v219
	ds_bpermute_b32 v217, v201, v219
	v_cmp_lt_i32_e32 vcc, 0, v188
	v_cmp_eq_u32_e64 s[98:99], 0, v188
	v_cmp_eq_u32_e64 s[100:101], 1, v188
	s_waitcnt lgkmcnt(0)
	s_nop 1
	v_cndmask_b32_e64 v217, v217, v206, s[100:101]
	v_cndmask_b32_e64 v217, v217, v210, s[98:99]
	v_cndmask_b32_e64 v216, v216, v206, s[98:99]
	ds_bpermute_b32 v210, v204, v219
	ds_bpermute_b32 v206, v203, v219
	ds_bpermute_b32 v220, v200, v218
	ds_bpermute_b32 v221, v201, v218
	v_cmp_lt_i32_e32 vcc, 0, v188
	v_cmp_eq_u32_e64 s[98:99], 0, v188
	v_cmp_eq_u32_e64 s[100:101], 1, v188
	s_waitcnt lgkmcnt(0)
	s_nop 1
	v_cndmask_b32_e64 v221, v221, v207, s[100:101]
	v_cndmask_b32_e64 v221, v221, v211, s[98:99]
	v_cndmask_b32_e64 v220, v220, v207, s[98:99]
	ds_bpermute_b32 v211, v204, v218
	ds_bpermute_b32 v207, v203, v218
	ds_bpermute_b32 v218, v200, v213
	ds_bpermute_b32 v219, v201, v213
	v_cmp_lt_i32_e32 vcc, 0, v188
	v_cmp_eq_u32_e64 s[98:99], 0, v188
	v_cmp_eq_u32_e64 s[100:101], 1, v188
	s_waitcnt lgkmcnt(0)
	s_nop 1
	v_cndmask_b32_e64 v219, v219, v208, s[100:101]
	v_cndmask_b32_e64 v219, v219, v212, s[98:99]
	v_cndmask_b32_e64 v218, v218, v208, s[98:99]
	s_waitcnt lgkmcnt(0)
	v_lshlrev_b32_e32 v208, 16, v221
	s_waitcnt vmcnt(0)
	v_fma_f32 v208, v56, v208, v52
	v_lshlrev_b32_e32 v212, 16, v220
	v_fmac_f32_e32 v208, v48, v212
	v_fmac_f32_e32 v208, v148, v44
	v_and_b32_e32 v148, 0xffff0000, v221
	v_fma_f32 v148, v57, v148, v53
	v_and_b32_e32 v212, 0xffff0000, v220
	v_fmac_f32_e32 v148, v49, v212
	v_fmac_f32_e32 v148, v149, v45
	v_mul_f32_e32 v149, 0x3d372713, v208
	v_mul_f32_e32 v149, v208, v149
	v_mul_f32_e32 v212, 0x3d372713, v148
	v_fma_f32 v149, v208, v149, v208
	v_mul_f32_e32 v212, v148, v212
	v_mul_f32_e32 v149, 0xc0135761, v149
	v_fma_f32 v212, v148, v212, v148
	v_exp_f32_e32 v149, v149
	v_mul_f32_e32 v212, 0xc0135761, v212
	v_exp_f32_e32 v212, v212
	v_cmp_lt_i32_e32 vcc, 0, v188
	v_add_f32_e32 v149, 1.0, v149
	v_rcp_f32_e32 v149, v149
	v_add_f32_e32 v212, 1.0, v212
	v_rcp_f32_e32 v212, v212
	v_mul_f32_e32 v149, v208, v149
	v_mul_f32_e32 v208, v144, v149
	v_mul_f32_e32 v144, v148, v212
	v_lshlrev_b32_e32 v148, 16, v217
	v_fma_f32 v148, v78, v148, v62
	v_lshlrev_b32_e32 v149, 16, v216
	v_fmac_f32_e32 v148, v70, v149
	v_fmac_f32_e32 v148, v158, v74
	v_mul_f32_e32 v158, 0x3d372713, v148
	v_mul_f32_e32 v158, v148, v158
	v_fma_f32 v158, v148, v158, v148
	v_mul_f32_e32 v158, 0xc0135761, v158
	v_exp_f32_e32 v158, v158
	v_and_b32_e32 v149, 0xffff0000, v217
	v_fma_f32 v149, v79, v149, v63
	v_and_b32_e32 v212, 0xffff0000, v216
	v_add_f32_e32 v158, 1.0, v158
	v_rcp_f32_e32 v158, v158
	v_fmac_f32_e32 v149, v71, v212
	v_fmac_f32_e32 v149, v159, v75
	v_mul_f32_e32 v159, 0x3d372713, v149
	v_mul_f32_e32 v145, v145, v144
	v_mul_f32_e32 v144, v148, v158
	v_lshlrev_b32_e32 v148, 16, v215
	v_mul_f32_e32 v159, v149, v159
	v_mul_f32_e32 v158, v154, v144
	v_fma_f32 v148, v76, v148, v60
	v_lshlrev_b32_e32 v154, 16, v214
	v_fma_f32 v159, v149, v159, v149
	v_fmac_f32_e32 v148, v68, v154
	v_and_b32_e32 v154, 0xffff0000, v215
	v_mul_f32_e32 v159, 0xc0135761, v159
	v_fmac_f32_e32 v148, v156, v72
	v_fma_f32 v154, v77, v154, v61
	v_and_b32_e32 v156, 0xffff0000, v214
	v_exp_f32_e32 v159, v159
	v_fmac_f32_e32 v154, v69, v156
	v_fmac_f32_e32 v154, v157, v73
	v_mul_f32_e32 v156, 0x3d372713, v148
	v_mul_f32_e32 v156, v148, v156
	v_mul_f32_e32 v157, 0x3d372713, v154
	v_fma_f32 v156, v148, v156, v148
	v_mul_f32_e32 v157, v154, v157
	v_add_f32_e32 v144, 1.0, v159
	v_mul_f32_e32 v156, 0xc0135761, v156
	v_fma_f32 v157, v154, v157, v154
	v_rcp_f32_e32 v144, v144
	v_exp_f32_e32 v156, v156
	v_mul_f32_e32 v157, 0xc0135761, v157
	v_exp_f32_e32 v157, v157
	v_mul_f32_e32 v144, v149, v144
	v_add_f32_e32 v149, 1.0, v156
	v_rcp_f32_e32 v149, v149
	v_add_f32_e32 v156, 1.0, v157
	v_rcp_f32_e32 v156, v156
	v_mul_f32_e32 v157, v155, v144
	v_mul_f32_e32 v144, v148, v149
	v_mul_f32_e32 v152, v152, v144
	v_mul_f32_e32 v144, v154, v156
	v_mul_f32_e32 v156, v153, v144
	v_and_b32_e32 v144, 0xffff0000, v219
	v_and_b32_e32 v149, 0xffff0000, v218
	v_mov_b32_e32 v154, v151
	v_mov_b32_e32 v155, v51
	v_mov_b32_e32 v148, v47
	v_fma_f32 v159, v59, v144, v55
	v_pk_mul_f32 v[148:149], v[154:155], v[148:149]
	v_mov_b32_e32 v144, v47
	v_add_f32_e32 v47, v159, v149
	v_add_f32_e32 v155, v148, v47
	v_mul_f32_e32 v47, 0x3d372713, v155
	v_mul_f32_e32 v47, v155, v47
	v_fma_f32 v47, v155, v47, v155
	v_mul_f32_e32 v47, 0xc0135761, v47
	v_exp_f32_e32 v159, v47
	v_lshlrev_b32_e32 v47, 16, v219
	v_fma_f32 v154, v58, v47, v54
	v_lshlrev_b32_e32 v47, 16, v218
	v_mov_b32_e32 v151, v50
	v_pk_mul_f32 v[148:149], v[150:151], v[46:47]
	v_mov_b64_e32 v[150:151], s[14:15]
	v_add_f32_e32 v47, v154, v149
	v_add_f32_e32 v47, v148, v47
	v_mul_f32_e32 v148, 0x3d372713, v47
	v_mul_f32_e32 v148, v47, v148
	v_fma_f32 v148, v47, v148, v47
	v_mul_f32_e32 v148, 0xc0135761, v148
	v_exp_f32_e32 v148, v148
	v_add_f32_e32 v149, 1.0, v159
	v_rcp_f32_e32 v149, v149
	v_or_b32_e32 v159, 16, v202
	v_add_f32_e32 v148, 1.0, v148
	v_rcp_f32_e32 v148, v148
	v_mul_f32_e32 v149, v155, v149
	v_mad_i64_i32 v[150:151], s[62:63], v159, s91, v[150:151]
	v_mul_f32_e32 v47, v47, v148
	v_mul_f32_e32 v149, v147, v149
	v_mul_f32_e32 v47, v146, v47
	v_cvt_pk_bf16_f32 v146, v152, v156
	v_lshl_add_u64 v[150:151], v[180:181], 1, v[150:151]
	ds_bpermute_b32 v153, v204, v213
	ds_bpermute_b32 v154, v203, v213
	v_cvt_pk_bf16_f32 v147, v158, v157
	v_cvt_pk_bf16_f32 v148, v208, v145
	v_cvt_pk_bf16_f32 v149, v47, v149
	global_store_dwordx4 v[150:151], v[146:149], off
	s_nop 1
	v_cvt_pk_bf16_f32 v146, v140, v141
	ds_bpermute_b32 v47, v200, v146
	ds_bpermute_b32 v145, v201, v146
	v_cvt_pk_bf16_f32 v147, v142, v143
	v_cvt_pk_bf16_f32 v148, v132, v133
	v_cvt_pk_bf16_f32 v152, v134, v135
	v_cmp_eq_u32_e64 s[98:99], 0, v188
	v_cmp_eq_u32_e64 s[100:101], 1, v188
	s_waitcnt lgkmcnt(0)
; __device__ __forceinline__ unsigned cvt_pk_bf16(float lo, float hi) { unsigned r; asm volatile("v_cvt_pk_bf16_f32 %0, %1, %2" : "=v"(r) : "v"(lo), "v"(hi)); return r; }
; __device__ __forceinline__ float gelu_tanh_f(float x) { const float y = -2.3022081983651455f * (x + 0.044715f * x * x * x); return x * __builtin_amdgcn_rcpf(1.f + __builtin_amdgcn_exp2f(y)); }
;     __device__ __forceinline__ void operator()(const f32x4 (&acc)[2][2][4][2], const Unit& u, int wr, int wc, int fr, int fq) const {
;     ...
;                 for (int q = 0; q < 4; ++q) {
;                     unsigned g1 = (unsigned)__shfl_up((int)pk[q], 1, 16), g2 = (unsigned)__shfl_up((int)pk[q], 2, 16);
;                     if (fr == 0) { g1 = l15[q]; g2 = l14[q]; } else if (fr == 1) { g2 = l15[q]; }
;                     const unsigned n14 = (unsigned)__shfl((int)pk[q], 14, 16), n15 = (unsigned)__shfl((int)pk[q], 15, 16);
;                     l14[q] = n14; l15[q] = n15;
;                     const int n = q >> 1, j = (q & 1) * 2, e = 2 * q;
;                     const float x0 = bb[e] + w0[e] * __uint_as_float(g2 << 16) + w1[e] * __uint_as_float(g1 << 16) + w2[e] * acc[ai][0][m][n][j];
;                     const float x1 = bb[e + 1] + w0[e + 1] * __uint_as_float(g2 & 0xffff0000u) + w1[e + 1] * __uint_as_float(g1 & 0xffff0000u) + w2[e + 1] * acc[ai][0][m][n][j + 1];
;                     hv[e] = gelu_tanh_f(x0) * acc[ai][1][m][n][j]; hv[e + 1] = gelu_tanh_f(x1) * acc[ai][1][m][n][j + 1];
;                 }
;                 const bool first2 = (slab == 0 && m == 0 && fr < 2);
;                 if (!first2) { u32x4 w; w.x = cvt_pk_bf16(hv[0], hv[1]); w.y = cvt_pk_bf16(hv[2], hv[3]); w.z = cvt_pk_bf16(hv[4], hv[5]); w.w = cvt_pk_bf16(hv[6], hv[7]);
;                     *(u32x4*)(H + (size_t)row * ldh + f0) = w; }
	s_nop 1
	v_cndmask_b32_e64 v145, v145, v205, s[100:101]
	v_cndmask_b32_e64 v145, v145, v209, s[98:99]
	v_cndmask_b32_e64 v47, v47, v205, s[98:99]
	ds_bpermute_b32 v149, v204, v146
	ds_bpermute_b32 v146, v203, v146
	ds_bpermute_b32 v155, v200, v147
	ds_bpermute_b32 v156, v201, v147
	v_cmp_lt_i32_e32 vcc, 0, v188
	v_cmp_eq_u32_e64 s[98:99], 0, v188
	v_cmp_eq_u32_e64 s[100:101], 1, v188
	s_waitcnt lgkmcnt(0)
	s_nop 1
	v_cndmask_b32_e64 v156, v156, v206, s[100:101]
	v_cndmask_b32_e64 v156, v156, v210, s[98:99]
	v_cndmask_b32_e64 v155, v155, v206, s[98:99]
	ds_bpermute_b32 v150, v204, v147
	ds_bpermute_b32 v147, v203, v147
	ds_bpermute_b32 v159, v200, v148
	ds_bpermute_b32 v205, v201, v148
	v_cmp_lt_i32_e32 vcc, 0, v188
	v_cmp_eq_u32_e64 s[98:99], 0, v188
	v_cmp_eq_u32_e64 s[100:101], 1, v188
	s_waitcnt lgkmcnt(0)
	s_nop 1
	v_cndmask_b32_e64 v205, v205, v207, s[100:101]
	v_cndmask_b32_e64 v205, v205, v211, s[98:99]
	v_cndmask_b32_e64 v159, v159, v207, s[98:99]
	ds_bpermute_b32 v151, v204, v148
	ds_bpermute_b32 v148, v203, v148
	ds_bpermute_b32 v157, v200, v152
	ds_bpermute_b32 v158, v201, v152
	v_cmp_lt_i32_e32 vcc, 0, v188
	v_cmp_eq_u32_e64 s[98:99], 0, v188
	v_cmp_eq_u32_e64 s[100:101], 1, v188
	s_waitcnt lgkmcnt(0)
	s_nop 1
	v_cndmask_b32_e64 v158, v158, v154, s[100:101]
	v_cndmask_b32_e64 v158, v158, v153, s[98:99]
	v_cndmask_b32_e64 v157, v157, v154, s[98:99]
	s_waitcnt lgkmcnt(4)
	v_lshlrev_b32_e32 v153, 16, v205
	v_fma_f32 v153, v56, v153, v52
	v_lshlrev_b32_e32 v154, 16, v159
	v_fmac_f32_e32 v153, v48, v154
	v_fmac_f32_e32 v153, v132, v44
	v_and_b32_e32 v132, 0xffff0000, v205
	v_fma_f32 v132, v57, v132, v53
	v_and_b32_e32 v154, 0xffff0000, v159
	v_fmac_f32_e32 v132, v49, v154
	v_fmac_f32_e32 v132, v133, v45
	v_mul_f32_e32 v133, 0x3d372713, v153
	v_mul_f32_e32 v133, v153, v133
	v_fma_f32 v133, v153, v133, v153
	v_mul_f32_e32 v133, 0xc0135761, v133
	v_exp_f32_e32 v133, v133
	v_mul_f32_e32 v154, 0x3d372713, v132
	v_mul_f32_e32 v154, v132, v154
	v_fma_f32 v154, v132, v154, v132
	v_add_f32_e32 v133, 1.0, v133
	v_rcp_f32_e32 v133, v133
	v_mul_f32_e32 v154, 0xc0135761, v154
	v_exp_f32_e32 v154, v154
	v_cmp_lt_i32_e32 vcc, 0, v188
	v_mul_f32_e32 v133, v153, v133
	v_mul_f32_e32 v128, v128, v133
	v_lshlrev_b32_e32 v133, 16, v156
	v_fma_f32 v133, v78, v133, v62
	v_lshlrev_b32_e32 v153, 16, v155
	v_fmac_f32_e32 v133, v70, v153
	v_fmac_f32_e32 v133, v142, v74
	v_mul_f32_e32 v153, 0x3d372713, v133
	v_add_f32_e32 v154, 1.0, v154
	v_mul_f32_e32 v153, v133, v153
	v_rcp_f32_e32 v154, v154
	v_fma_f32 v153, v133, v153, v133
	v_mul_f32_e32 v153, 0xc0135761, v153
	v_exp_f32_e32 v153, v153
	v_and_b32_e32 v142, 0xffff0000, v156
	v_mul_f32_e32 v132, v132, v154
	v_fma_f32 v142, v79, v142, v63
	v_and_b32_e32 v154, 0xffff0000, v155
	v_fmac_f32_e32 v142, v71, v154
	v_fmac_f32_e32 v142, v143, v75
	v_add_f32_e32 v143, 1.0, v153
	v_rcp_f32_e32 v143, v143
	v_mul_f32_e32 v154, v129, v132
	v_lshlrev_b32_e32 v132, 16, v145
	v_fma_f32 v132, v76, v132, v60
	v_mul_f32_e32 v129, v133, v143
	v_lshlrev_b32_e32 v133, 16, v47
	v_fmac_f32_e32 v132, v68, v133
	v_and_b32_e32 v133, 0xffff0000, v145
	v_fma_f32 v133, v77, v133, v61
	v_and_b32_e32 v47, 0xffff0000, v47
	v_fmac_f32_e32 v132, v140, v72
	v_fmac_f32_e32 v133, v69, v47
	v_fmac_f32_e32 v133, v141, v73
	v_mul_f32_e32 v47, 0x3d372713, v132
	v_mul_f32_e32 v47, v132, v47
	v_mul_f32_e32 v140, 0x3d372713, v133
	v_fma_f32 v47, v132, v47, v132
	v_mul_f32_e32 v140, v133, v140
	v_mul_f32_e32 v47, 0xc0135761, v47
	v_fma_f32 v140, v133, v140, v133
	v_exp_f32_e32 v47, v47
	v_mul_f32_e32 v140, 0xc0135761, v140
	v_exp_f32_e32 v140, v140
	v_mul_f32_e32 v153, 0x3d372713, v142
	v_add_f32_e32 v47, 1.0, v47
	v_rcp_f32_e32 v47, v47
	v_add_f32_e32 v140, 1.0, v140
	v_rcp_f32_e32 v140, v140
	v_mul_f32_e32 v153, v142, v153
	v_fma_f32 v153, v142, v153, v142
	v_mul_f32_e32 v47, v132, v47
	v_mul_f32_e32 v153, 0xc0135761, v153
	v_mul_f32_e32 v136, v136, v47
	v_mul_f32_e32 v47, v133, v140
	v_exp_f32_e32 v153, v153
	v_mul_f32_e32 v137, v137, v47
	s_waitcnt lgkmcnt(0)
	v_and_b32_e32 v47, 0xffff0000, v158
	v_and_b32_e32 v145, 0xffff0000, v157
	v_mov_b32_e32 v132, v135
	v_mov_b32_e32 v133, v51
	v_fma_f32 v47, v59, v47, v55
	v_pk_mul_f32 v[132:133], v[132:133], v[144:145]
	v_mul_f32_e32 v138, v138, v129
	v_add_f32_e32 v47, v47, v133
	v_add_f32_e32 v140, v132, v47
	v_add_f32_e32 v129, 1.0, v153
	v_mul_f32_e32 v47, 0x3d372713, v140
	v_rcp_f32_e32 v129, v129
	v_mul_f32_e32 v47, v140, v47
	v_fma_f32 v47, v140, v47, v140
	v_mul_f32_e32 v47, 0xc0135761, v47
	v_exp_f32_e32 v141, v47
	v_lshlrev_b32_e32 v47, 16, v158
	v_mul_f32_e32 v129, v142, v129
	v_fma_f32 v142, v58, v47, v54
	v_lshlrev_b32_e32 v47, 16, v157
	v_mov_b32_e32 v135, v50
	v_pk_mul_f32 v[132:133], v[134:135], v[46:47]
	v_add_f32_e32 v134, 1.0, v141
	v_add_f32_e32 v47, v142, v133
	v_add_f32_e32 v47, v132, v47
	v_mul_f32_e32 v132, 0x3d372713, v47
	v_mul_f32_e32 v132, v47, v132
	v_fma_f32 v132, v47, v132, v47
	v_mul_f32_e32 v132, 0xc0135761, v132
	v_exp_f32_e32 v133, v132
	v_rcp_f32_e32 v134, v134
	v_mul_f32_e32 v139, v139, v129
	v_or_b32_e32 v141, 32, v202
	v_add_f32_e32 v133, 1.0, v133
	v_rcp_f32_e32 v133, v133
	v_mul_f32_e32 v134, v140, v134
	v_mul_f32_e32 v131, v131, v134
	v_cvt_pk_bf16_f32 v134, v136, v137
	v_mul_f32_e32 v47, v47, v133
	v_mul_f32_e32 v47, v130, v47
	v_cvt_pk_bf16_f32 v135, v138, v139
	v_cvt_pk_bf16_f32 v136, v128, v154
	v_cvt_pk_bf16_f32 v137, v47, v131
	v_mov_b64_e32 v[130:131], s[14:15]
	v_mad_i64_i32 v[130:131], s[62:63], v141, s91, v[130:131]
	v_lshl_add_u64 v[130:131], v[180:181], 1, v[130:131]
	global_store_dwordx4 v[130:131], v[134:137], off
	v_cvt_pk_bf16_f32 v128, v124, v125
	ds_bpermute_b32 v129, v204, v152
	ds_bpermute_b32 v132, v203, v152
	ds_bpermute_b32 v47, v200, v128
	ds_bpermute_b32 v128, v201, v128
	v_cvt_pk_bf16_f32 v131, v126, v127
	v_cvt_pk_bf16_f32 v133, v120, v121
	v_cvt_pk_bf16_f32 v134, v122, v123
	v_cmp_eq_u32_e64 s[98:99], 0, v188
	v_cmp_eq_u32_e64 s[100:101], 1, v188
	s_waitcnt lgkmcnt(0)
; __device__ __forceinline__ unsigned cvt_pk_bf16(float lo, float hi) { unsigned r; asm volatile("v_cvt_pk_bf16_f32 %0, %1, %2" : "=v"(r) : "v"(lo), "v"(hi)); return r; }
; __device__ __forceinline__ float gelu_tanh_f(float x) { const float y = -2.3022081983651455f * (x + 0.044715f * x * x * x); return x * __builtin_amdgcn_rcpf(1.f + __builtin_amdgcn_exp2f(y)); }
;     __device__ __forceinline__ void operator()(const f32x4 (&acc)[2][2][4][2], const Unit& u, int wr, int wc, int fr, int fq) const {
;     ...
;                 for (int q = 0; q < 4; ++q) {
;                     unsigned g1 = (unsigned)__shfl_up((int)pk[q], 1, 16), g2 = (unsigned)__shfl_up((int)pk[q], 2, 16);
;                     if (fr == 0) { g1 = l15[q]; g2 = l14[q]; } else if (fr == 1) { g2 = l15[q]; }
;                     const unsigned n14 = (unsigned)__shfl((int)pk[q], 14, 16), n15 = (unsigned)__shfl((int)pk[q], 15, 16);
;                     l14[q] = n14; l15[q] = n15;
;                     const int n = q >> 1, j = (q & 1) * 2, e = 2 * q;
;                     const float x0 = bb[e] + w0[e] * __uint_as_float(g2 << 16) + w1[e] * __uint_as_float(g1 << 16) + w2[e] * acc[ai][0][m][n][j];
;                     const float x1 = bb[e + 1] + w0[e + 1] * __uint_as_float(g2 & 0xffff0000u) + w1[e + 1] * __uint_as_float(g1 & 0xffff0000u) + w2[e + 1] * acc[ai][0][m][n][j + 1];
;                     hv[e] = gelu_tanh_f(x0) * acc[ai][1][m][n][j]; hv[e + 1] = gelu_tanh_f(x1) * acc[ai][1][m][n][j + 1];
;                 }
;                 const bool first2 = (slab == 0 && m == 0 && fr < 2);
;                 if (!first2) { u32x4 w; w.x = cvt_pk_bf16(hv[0], hv[1]); w.y = cvt_pk_bf16(hv[2], hv[3]); w.z = cvt_pk_bf16(hv[4], hv[5]); w.w = cvt_pk_bf16(hv[6], hv[7]);
;                     *(u32x4*)(H + (size_t)row * ldh + f0) = w; }
;                 else { float* p = hp + (size_t)fr * ff; *(f32x4*)p = acc[0][0][0][0]; *(f32x4*)(p + 4) = acc[0][0][0][1];
;                     float* pu = hp + (size_t)(4 + fr) * ff; *(f32x4*)pu = acc[0][1][0][0]; *(f32x4*)(pu + 4) = acc[0][1][0][1]; }
;                 if (slab == 3 && m == 3 && fr >= 14) { float* p = hp + (size_t)(2 + fr - 14) * ff; *(f32x4*)p = acc[1][0][3][0]; *(f32x4*)(p + 4) = acc[1][0][3][1]; }
	s_nop 1
	v_cndmask_b32_e64 v128, v128, v146, s[100:101]
	v_cndmask_b32_e64 v128, v128, v149, s[98:99]
	v_cndmask_b32_e64 v47, v47, v146, s[98:99]
	ds_bpermute_b32 v130, v200, v131
	ds_bpermute_b32 v131, v201, v131
	v_cmp_lt_i32_e32 vcc, 0, v188
	v_cmp_eq_u32_e64 s[98:99], 0, v188
	v_cmp_eq_u32_e64 s[100:101], 1, v188
	s_waitcnt lgkmcnt(0)
	s_nop 1
	v_cndmask_b32_e64 v131, v131, v147, s[100:101]
	v_cndmask_b32_e64 v131, v131, v150, s[98:99]
	v_cndmask_b32_e64 v130, v130, v147, s[98:99]
	ds_bpermute_b32 v135, v200, v133
	ds_bpermute_b32 v136, v201, v133
	v_cmp_lt_i32_e32 vcc, 0, v188
	v_cmp_eq_u32_e64 s[98:99], 0, v188
	v_cmp_eq_u32_e64 s[100:101], 1, v188
	s_waitcnt lgkmcnt(0)
	s_nop 1
	v_cndmask_b32_e64 v136, v136, v148, s[100:101]
	v_cndmask_b32_e64 v136, v136, v151, s[98:99]
	v_cndmask_b32_e64 v135, v135, v148, s[98:99]
	ds_bpermute_b32 v133, v200, v134
	ds_bpermute_b32 v134, v201, v134
	v_cmp_lt_i32_e32 vcc, 0, v188
	v_cmp_eq_u32_e64 s[98:99], 0, v188
	v_cmp_eq_u32_e64 s[100:101], 1, v188
	s_waitcnt lgkmcnt(0)
	s_nop 1
	v_cndmask_b32_e64 v134, v134, v132, s[100:101]
	v_cndmask_b32_e64 v134, v134, v129, s[98:99]
	v_cndmask_b32_e64 v133, v133, v132, s[98:99]
	s_waitcnt lgkmcnt(2)
	v_lshlrev_b32_e32 v129, 16, v136
	v_fma_f32 v129, v56, v129, v52
	v_lshlrev_b32_e32 v132, 16, v135
	v_fmac_f32_e32 v129, v48, v132
	v_fmac_f32_e32 v129, v120, v44
	v_and_b32_e32 v120, 0xffff0000, v136
	v_fma_f32 v120, v57, v120, v53
	v_and_b32_e32 v132, 0xffff0000, v135
	v_fmac_f32_e32 v120, v49, v132
	v_fmac_f32_e32 v120, v121, v45
	v_mul_f32_e32 v121, 0x3d372713, v129
	v_mul_f32_e32 v121, v129, v121
	v_mul_f32_e32 v132, 0x3d372713, v120
	v_fma_f32 v121, v129, v121, v129
	v_mul_f32_e32 v132, v120, v132
	v_mul_f32_e32 v121, 0xc0135761, v121
	v_fma_f32 v132, v120, v132, v120
	v_exp_f32_e32 v121, v121
	v_mul_f32_e32 v132, 0xc0135761, v132
	v_exp_f32_e32 v132, v132
	s_waitcnt lgkmcnt(1)
	v_and_b32_e32 v145, 0xffff0000, v133
	v_add_f32_e32 v121, 1.0, v121
	v_rcp_f32_e32 v121, v121
	v_add_f32_e32 v132, 1.0, v132
	v_rcp_f32_e32 v132, v132
	v_mul_f32_e32 v121, v129, v121
	v_mul_f32_e32 v121, v112, v121
	v_mul_f32_e32 v112, v120, v132
	v_lshlrev_b32_e32 v120, 16, v131
	v_fma_f32 v120, v78, v120, v62
	v_lshlrev_b32_e32 v129, 16, v130
	v_fmac_f32_e32 v120, v70, v129
	v_fmac_f32_e32 v120, v126, v74
	v_mul_f32_e32 v129, 0x3d372713, v120
	v_mul_f32_e32 v129, v120, v129
	v_fma_f32 v129, v120, v129, v120
	v_mul_f32_e32 v129, 0xc0135761, v129
	v_exp_f32_e32 v129, v129
	v_and_b32_e32 v126, 0xffff0000, v131
	v_fma_f32 v126, v79, v126, v63
	v_and_b32_e32 v130, 0xffff0000, v130
	v_fmac_f32_e32 v126, v71, v130
	v_fmac_f32_e32 v126, v127, v75
	v_add_f32_e32 v127, 1.0, v129
	v_rcp_f32_e32 v127, v127
	v_mul_f32_e32 v130, v113, v112
	v_lshlrev_b32_e32 v113, 16, v128
	v_fma_f32 v113, v76, v113, v60
	v_mul_f32_e32 v112, v120, v127
	v_lshlrev_b32_e32 v120, 16, v47
	v_fmac_f32_e32 v113, v68, v120
	v_and_b32_e32 v120, 0xffff0000, v128
	v_fmac_f32_e32 v113, v124, v72
	v_fma_f32 v120, v77, v120, v61
	v_and_b32_e32 v47, 0xffff0000, v47
	v_mul_f32_e32 v129, 0x3d372713, v126
	v_fmac_f32_e32 v120, v69, v47
	v_mul_f32_e32 v47, 0x3d372713, v113
	v_mul_f32_e32 v129, v126, v129
	v_mul_f32_e32 v47, v113, v47
	v_fma_f32 v129, v126, v129, v126
	v_fma_f32 v47, v113, v47, v113
	v_mul_f32_e32 v129, 0xc0135761, v129
	v_fmac_f32_e32 v120, v125, v73
	v_mul_f32_e32 v47, 0xc0135761, v47
	v_exp_f32_e32 v129, v129
	v_exp_f32_e32 v47, v47
	v_mul_f32_e32 v124, 0x3d372713, v120
	v_mul_f32_e32 v124, v120, v124
	v_fma_f32 v124, v120, v124, v120
	v_mul_f32_e32 v124, 0xc0135761, v124
	v_mul_f32_e32 v118, v118, v112
	v_add_f32_e32 v112, 1.0, v129
	v_exp_f32_e32 v124, v124
	v_add_f32_e32 v47, 1.0, v47
	v_rcp_f32_e32 v112, v112
	v_rcp_f32_e32 v47, v47
	v_add_f32_e32 v124, 1.0, v124
	v_rcp_f32_e32 v124, v124
	v_mul_f32_e32 v112, v126, v112
	v_mul_f32_e32 v47, v113, v47
	v_mul_f32_e32 v119, v119, v112
	v_mul_f32_e32 v116, v116, v47
	s_waitcnt lgkmcnt(0)
	v_and_b32_e32 v47, 0xffff0000, v134
	v_mov_b32_e32 v112, v123
	v_mov_b32_e32 v113, v51
	v_fma_f32 v47, v59, v47, v55
	v_pk_mul_f32 v[112:113], v[112:113], v[144:145]
	v_mul_f32_e32 v120, v120, v124
	v_add_f32_e32 v47, v47, v113
	v_add_f32_e32 v124, v112, v47
	v_mul_f32_e32 v47, 0x3d372713, v124
	v_mul_f32_e32 v47, v124, v47
	v_fma_f32 v47, v124, v47, v124
	v_mul_f32_e32 v47, 0xc0135761, v47
	v_exp_f32_e32 v125, v47
	v_lshlrev_b32_e32 v47, 16, v134
	v_fma_f32 v126, v58, v47, v54
	v_lshlrev_b32_e32 v47, 16, v133
	v_mov_b32_e32 v123, v50
	v_pk_mul_f32 v[112:113], v[122:123], v[46:47]
	s_nop 0
	v_add_f32_e32 v47, v126, v113
	v_add_f32_e32 v47, v112, v47
	v_mul_f32_e32 v112, 0x3d372713, v47
	v_mul_f32_e32 v112, v47, v112
	v_fma_f32 v112, v47, v112, v47
	v_mul_f32_e32 v112, 0xc0135761, v112
	v_exp_f32_e32 v112, v112
	v_mul_f32_e32 v113, v117, v120
	v_add_f32_e32 v117, 1.0, v125
	v_rcp_f32_e32 v117, v117
	v_add_f32_e32 v112, 1.0, v112
	v_rcp_f32_e32 v112, v112
	v_or_b32_e32 v120, 48, v202
	v_mul_f32_e32 v117, v124, v117
	v_mul_f32_e32 v115, v115, v117
	v_mul_f32_e32 v47, v47, v112
	v_cvt_pk_bf16_f32 v112, v116, v113
	v_mov_b64_e32 v[116:117], s[14:15]
	v_mad_i64_i32 v[116:117], s[62:63], v120, s91, v[116:117]
	v_cvt_pk_bf16_f32 v113, v118, v119
	v_lshl_add_u64 v[116:117], v[180:181], 1, v[116:117]
	v_mul_f32_e32 v47, v114, v47
	v_cvt_pk_bf16_f32 v114, v121, v130
	v_cvt_pk_bf16_f32 v115, v47, v115
	global_store_dwordx4 v[116:117], v[112:115], off
	s_nop 1
	v_lshl_add_u64 v[112:113], v[186:187], 0, v[170:171]
	s_and_saveexec_b64 s[62:63], s[26:27]
	s_cbranch_execz .LBB0_1297
	global_store_dwordx4 v[112:113], v[12:15], off
	global_store_dwordx4 v[112:113], v[4:7], off offset:16

; __device__ __forceinline__ unsigned cvt_pk_bf16(float lo, float hi) { unsigned r; asm volatile("v_cvt_pk_bf16_f32 %0, %1, %2" : "=v"(r) : "v"(lo), "v"(hi)); return r; }
; __device__ __forceinline__ float gelu_tanh_f(float x) { const float y = -2.3022081983651455f * (x + 0.044715f * x * x * x); return x * __builtin_amdgcn_rcpf(1.f + __builtin_amdgcn_exp2f(y)); }
;     __device__ __forceinline__ void operator()(const f32x4 (&acc)[2][2][4][2], const Unit& u, int wr, int wc, int fr, int fq) const {
;     ...
;             for (int m = 0; m < 4; ++m) {
;                 const int row = u.pm * BM + ai * HALF + wr * 64 + m * 16 + fr;
;                 unsigned pk[4];
;                 pk[0] = cvt_pk_bf16(acc[ai][0][m][0][0], acc[ai][0][m][0][1]); pk[1] = cvt_pk_bf16(acc[ai][0][m][0][2], acc[ai][0][m][0][3]);
;                 pk[2] = cvt_pk_bf16(acc[ai][0][m][1][0], acc[ai][0][m][1][1]); pk[3] = cvt_pk_bf16(acc[ai][0][m][1][2], acc[ai][0][m][1][3]);
;                 float hv[8];
; #pragma unroll
;                 for (int q = 0; q < 4; ++q) {
;                     unsigned g1 = (unsigned)__shfl_up((int)pk[q], 1, 16), g2 = (unsigned)__shfl_up((int)pk[q], 2, 16);
;                     if (fr == 0) { g1 = l15[q]; g2 = l14[q]; } else if (fr == 1) { g2 = l15[q]; }
;                     const unsigned n14 = (unsigned)__shfl((int)pk[q], 14, 16), n15 = (unsigned)__shfl((int)pk[q], 15, 16);
;                     l14[q] = n14; l15[q] = n15;
;                     const int n = q >> 1, j = (q & 1) * 2, e = 2 * q;
;                     const float x0 = bb[e] + w0[e] * __uint_as_float(g2 << 16) + w1[e] * __uint_as_float(g1 << 16) + w2[e] * acc[ai][0][m][n][j];
;                     const float x1 = bb[e + 1] + w0[e + 1] * __uint_as_float(g2 & 0xffff0000u) + w1[e + 1] * __uint_as_float(g1 & 0xffff0000u) + w2[e + 1] * acc[ai][0][m][n][j + 1];
;                     hv[e] = gelu_tanh_f(x0) * acc[ai][1][m][n][j]; hv[e + 1] = gelu_tanh_f(x1) * acc[ai][1][m][n][j + 1];
;                 }
;                 const bool first2 = (slab == 0 && m == 0 && fr < 2);
;                 if (!first2) { u32x4 w; w.x = cvt_pk_bf16(hv[0], hv[1]); w.y = cvt_pk_bf16(hv[2], hv[3]); w.z = cvt_pk_bf16(hv[4], hv[5]); w.w = cvt_pk_bf16(hv[6], hv[7]);
;                     *(u32x4*)(H + (size_t)row * ldh + f0) = w; }
.LBB0_1299:
	v_cvt_pk_bf16_f32 v123, v108, v109
	ds_bpermute_b32 v47, v200, v123
	ds_bpermute_b32 v122, v201, v123
	v_cmp_lt_i32_e32 vcc, 0, v188
	v_cvt_pk_bf16_f32 v127, v110, v111
	v_cvt_pk_bf16_f32 v126, v96, v97
	v_cvt_pk_bf16_f32 v124, v98, v99
	v_cmp_eq_u32_e64 s[98:99], 0, v188
	v_cmp_eq_u32_e64 s[100:101], 1, v188
	s_waitcnt lgkmcnt(0)
	s_nop 1
	v_cndmask_b32_e64 v122, v122, v118, s[100:101]
	v_cndmask_b32_e64 v122, v122, v114, s[98:99]
	v_cndmask_b32_e64 v47, v47, v118, s[98:99]
	ds_bpermute_b32 v118, v204, v123
	ds_bpermute_b32 v114, v203, v123
	ds_bpermute_b32 v123, v200, v127
	ds_bpermute_b32 v125, v201, v127
	v_cmp_lt_i32_e32 vcc, 0, v188
	v_cmp_eq_u32_e64 s[98:99], 0, v188
	v_cmp_eq_u32_e64 s[100:101], 1, v188
	s_waitcnt lgkmcnt(0)
	s_nop 1
	v_cndmask_b32_e64 v125, v125, v119, s[100:101]
	v_cndmask_b32_e64 v125, v125, v115, s[98:99]
	v_cndmask_b32_e64 v123, v123, v119, s[98:99]
	ds_bpermute_b32 v119, v204, v127
	ds_bpermute_b32 v115, v203, v127
	ds_bpermute_b32 v128, v200, v126
	ds_bpermute_b32 v129, v201, v126
	v_cmp_lt_i32_e32 vcc, 0, v188
	v_cmp_eq_u32_e64 s[98:99], 0, v188
	v_cmp_eq_u32_e64 s[100:101], 1, v188
	s_waitcnt lgkmcnt(0)
	s_nop 1
	v_cndmask_b32_e64 v129, v129, v120, s[100:101]
	v_cndmask_b32_e64 v129, v129, v116, s[98:99]
	v_cndmask_b32_e64 v128, v128, v120, s[98:99]
	ds_bpermute_b32 v120, v204, v126
	ds_bpermute_b32 v116, v203, v126
	ds_bpermute_b32 v126, v200, v124
	ds_bpermute_b32 v127, v201, v124
	v_cmp_lt_i32_e32 vcc, 0, v188
	v_cmp_eq_u32_e64 s[98:99], 0, v188
	v_cmp_eq_u32_e64 s[100:101], 1, v188
	s_waitcnt lgkmcnt(0)
	s_nop 1
	v_cndmask_b32_e64 v127, v127, v121, s[100:101]
	v_cndmask_b32_e64 v127, v127, v117, s[98:99]
	v_cndmask_b32_e64 v126, v126, v121, s[98:99]
	ds_bpermute_b32 v121, v204, v124
	ds_bpermute_b32 v117, v203, v124
	s_and_saveexec_b64 s[62:63], s[44:45]
	s_xor_b64 s[62:63], exec, s[62:63]
	s_cbranch_execz .LBB0_1325
	s_waitcnt lgkmcnt(6)
	v_lshlrev_b32_e32 v124, 16, v129
	v_fma_f32 v124, v56, v124, v52
	v_lshlrev_b32_e32 v130, 16, v128
	v_fmac_f32_e32 v124, v48, v130
	v_fmac_f32_e32 v124, v96, v44
	v_and_b32_e32 v96, 0xffff0000, v129
	v_fma_f32 v96, v57, v96, v53
	v_and_b32_e32 v128, 0xffff0000, v128
	v_fmac_f32_e32 v96, v49, v128
	v_fmac_f32_e32 v96, v97, v45
	v_mul_f32_e32 v97, 0x3d372713, v124
	v_mul_f32_e32 v97, v124, v97
	v_mul_f32_e32 v128, 0x3d372713, v96
	v_fma_f32 v97, v124, v97, v124
	v_mul_f32_e32 v128, v96, v128
	v_mul_f32_e32 v97, 0xc0135761, v97
	v_fma_f32 v128, v96, v128, v96
	v_exp_f32_e32 v97, v97
	v_mul_f32_e32 v128, 0xc0135761, v128
	v_exp_f32_e32 v128, v128
	s_waitcnt lgkmcnt(3)
	v_and_b32_e32 v145, 0xffff0000, v126
	v_add_f32_e32 v97, 1.0, v97
	v_rcp_f32_e32 v97, v97
	v_add_f32_e32 v128, 1.0, v128
	v_rcp_f32_e32 v128, v128
	v_mul_f32_e32 v97, v124, v97
	v_mul_f32_e32 v97, v80, v97
	v_mul_f32_e32 v80, v96, v128
	v_lshlrev_b32_e32 v96, 16, v125
	v_fma_f32 v96, v78, v96, v62
	v_lshlrev_b32_e32 v124, 16, v123
	v_fmac_f32_e32 v96, v70, v124
	v_fmac_f32_e32 v96, v110, v74
	v_mul_f32_e32 v124, 0x3d372713, v96
	v_mul_f32_e32 v124, v96, v124
	v_fma_f32 v124, v96, v124, v96
	v_mul_f32_e32 v124, 0xc0135761, v124
	v_exp_f32_e32 v124, v124
	v_and_b32_e32 v110, 0xffff0000, v125
	v_fma_f32 v110, v79, v110, v63
	v_and_b32_e32 v123, 0xffff0000, v123
	v_fmac_f32_e32 v110, v71, v123
	v_fmac_f32_e32 v110, v111, v75
	v_add_f32_e32 v111, 1.0, v124
	v_rcp_f32_e32 v111, v111
	v_mul_f32_e32 v124, v81, v80
	v_lshlrev_b32_e32 v81, 16, v122
	v_fma_f32 v81, v76, v81, v60
	v_mul_f32_e32 v80, v96, v111
	v_lshlrev_b32_e32 v96, 16, v47
	v_fmac_f32_e32 v81, v68, v96
	v_and_b32_e32 v96, 0xffff0000, v122
	v_fmac_f32_e32 v81, v108, v72
	v_fma_f32 v96, v77, v96, v61
	v_and_b32_e32 v47, 0xffff0000, v47
	v_mul_f32_e32 v123, 0x3d372713, v110
	v_fmac_f32_e32 v96, v69, v47
	v_mul_f32_e32 v47, 0x3d372713, v81
	v_mul_f32_e32 v123, v110, v123
	v_mul_f32_e32 v47, v81, v47
	v_fma_f32 v123, v110, v123, v110
	v_fma_f32 v47, v81, v47, v81
	v_mul_f32_e32 v123, 0xc0135761, v123
	v_fmac_f32_e32 v96, v109, v73
	v_mul_f32_e32 v47, 0xc0135761, v47
	v_exp_f32_e32 v123, v123
	v_exp_f32_e32 v47, v47
	v_mul_f32_e32 v108, 0x3d372713, v96
	v_mul_f32_e32 v108, v96, v108
	v_fma_f32 v108, v96, v108, v96
	v_mul_f32_e32 v108, 0xc0135761, v108
	v_mul_f32_e32 v86, v86, v80
	v_add_f32_e32 v80, 1.0, v123
	v_exp_f32_e32 v108, v108
	v_add_f32_e32 v47, 1.0, v47
	v_rcp_f32_e32 v80, v80
	v_rcp_f32_e32 v47, v47
	v_add_f32_e32 v108, 1.0, v108
	v_rcp_f32_e32 v108, v108
	v_mul_f32_e32 v80, v110, v80
	v_mul_f32_e32 v47, v81, v47
	v_mul_f32_e32 v87, v87, v80
	v_mul_f32_e32 v84, v84, v47
	s_waitcnt lgkmcnt(2)
	v_and_b32_e32 v47, 0xffff0000, v127
	v_mov_b32_e32 v80, v99
	v_mov_b32_e32 v81, v51
	v_fma_f32 v47, v59, v47, v55
	v_pk_mul_f32 v[80:81], v[80:81], v[144:145]
	v_mul_f32_e32 v96, v96, v108
	v_add_f32_e32 v47, v47, v81
	v_add_f32_e32 v108, v80, v47
	v_mul_f32_e32 v47, 0x3d372713, v108
	v_mul_f32_e32 v47, v108, v47
	v_fma_f32 v47, v108, v47, v108
	v_mul_f32_e32 v47, 0xc0135761, v47
	v_exp_f32_e32 v109, v47
	v_lshlrev_b32_e32 v47, 16, v127
	v_fma_f32 v110, v58, v47, v54
	v_lshlrev_b32_e32 v47, 16, v126
	v_mov_b32_e32 v99, v50
	v_pk_mul_f32 v[80:81], v[98:99], v[46:47]
	s_nop 0
	v_add_f32_e32 v47, v110, v81
	v_add_f32_e32 v47, v80, v47
	v_mul_f32_e32 v80, 0x3d372713, v47
	v_mul_f32_e32 v80, v47, v80
	v_fma_f32 v80, v47, v80, v47
	v_mul_f32_e32 v80, 0xc0135761, v80
	v_exp_f32_e32 v80, v80
	v_mul_f32_e32 v81, v85, v96
	v_add_f32_e32 v85, 1.0, v109
	v_rcp_f32_e32 v85, v85
	v_add_f32_e32 v80, 1.0, v80
	v_rcp_f32_e32 v80, v80
	v_add_u32_e32 v96, 0x80, v202
	v_mul_f32_e32 v85, v108, v85
	v_mul_f32_e32 v83, v83, v85
	v_mul_f32_e32 v47, v47, v80
	v_cvt_pk_bf16_f32 v80, v84, v81
	v_mov_b64_e32 v[84:85], s[14:15]
	v_mad_i64_i32 v[84:85], s[64:65], v96, s91, v[84:85]
	v_lshl_add_u64 v[84:85], v[180:181], 1, v[84:85]
	v_mul_f32_e32 v47, v82, v47
	v_cvt_pk_bf16_f32 v81, v86, v87
	v_cvt_pk_bf16_f32 v82, v97, v124
	v_cvt_pk_bf16_f32 v83, v47, v83
	global_store_dwordx4 v[84:85], v[80:83], off

; __device__ __forceinline__ unsigned cvt_pk_bf16(float lo, float hi) { unsigned r; asm volatile("v_cvt_pk_bf16_f32 %0, %1, %2" : "=v"(r) : "v"(lo), "v"(hi)); return r; }
; __device__ __forceinline__ float gelu_tanh_f(float x) { const float y = -2.3022081983651455f * (x + 0.044715f * x * x * x); return x * __builtin_amdgcn_rcpf(1.f + __builtin_amdgcn_exp2f(y)); }
;     __device__ __forceinline__ void operator()(const f32x4 (&acc)[2][2][4][2], const Unit& u, int wr, int wc, int fr, int fq) const {
;     ...
;                 for (int q = 0; q < 4; ++q) {
;                     unsigned g1 = (unsigned)__shfl_up((int)pk[q], 1, 16), g2 = (unsigned)__shfl_up((int)pk[q], 2, 16);
;                     if (fr == 0) { g1 = l15[q]; g2 = l14[q]; } else if (fr == 1) { g2 = l15[q]; }
;                     const unsigned n14 = (unsigned)__shfl((int)pk[q], 14, 16), n15 = (unsigned)__shfl((int)pk[q], 15, 16);
;                     l14[q] = n14; l15[q] = n15;
;                     const int n = q >> 1, j = (q & 1) * 2, e = 2 * q;
;                     const float x0 = bb[e] + w0[e] * __uint_as_float(g2 << 16) + w1[e] * __uint_as_float(g1 << 16) + w2[e] * acc[ai][0][m][n][j];
;                     const float x1 = bb[e + 1] + w0[e + 1] * __uint_as_float(g2 & 0xffff0000u) + w1[e + 1] * __uint_as_float(g1 & 0xffff0000u) + w2[e + 1] * acc[ai][0][m][n][j + 1];
;                     hv[e] = gelu_tanh_f(x0) * acc[ai][1][m][n][j]; hv[e + 1] = gelu_tanh_f(x1) * acc[ai][1][m][n][j + 1];
;                 }
;                 const bool first2 = (slab == 0 && m == 0 && fr < 2);
;                 if (!first2) { u32x4 w; w.x = cvt_pk_bf16(hv[0], hv[1]); w.y = cvt_pk_bf16(hv[2], hv[3]); w.z = cvt_pk_bf16(hv[4], hv[5]); w.w = cvt_pk_bf16(hv[6], hv[7]);
;                     *(u32x4*)(H + (size_t)row * ldh + f0) = w; }
.LBB0_1327:
	s_or_b64 exec, exec, s[62:63]
	v_cvt_pk_bf16_f32 v80, v64, v65
	s_waitcnt lgkmcnt(14)
	ds_bpermute_b32 v47, v200, v80
	ds_bpermute_b32 v87, v201, v80
	v_cmp_lt_i32_e32 vcc, 0, v188
	v_cvt_pk_bf16_f32 v81, v66, v67
	v_cvt_pk_bf16_f32 v82, v36, v37
	v_cvt_pk_bf16_f32 v86, v38, v39
	v_cmp_eq_u32_e64 s[98:99], 0, v188
	v_cmp_eq_u32_e64 s[100:101], 1, v188
	s_waitcnt lgkmcnt(0)
	s_nop 1
	v_cndmask_b32_e64 v87, v87, v114, s[100:101]
	v_cndmask_b32_e64 v87, v87, v118, s[98:99]
	v_cndmask_b32_e64 v47, v47, v114, s[98:99]
	ds_bpermute_b32 v83, v204, v80
	ds_bpermute_b32 v80, v203, v80
	ds_bpermute_b32 v88, v200, v81
	ds_bpermute_b32 v89, v201, v81
	v_cmp_lt_i32_e32 vcc, 0, v188
	v_cmp_eq_u32_e64 s[98:99], 0, v188
	v_cmp_eq_u32_e64 s[100:101], 1, v188
	s_waitcnt lgkmcnt(0)
	s_nop 1
	v_cndmask_b32_e64 v89, v89, v115, s[100:101]
	v_cndmask_b32_e64 v89, v89, v119, s[98:99]
	v_cndmask_b32_e64 v88, v88, v115, s[98:99]
	ds_bpermute_b32 v84, v204, v81
	ds_bpermute_b32 v81, v203, v81
	ds_bpermute_b32 v92, v200, v82
	ds_bpermute_b32 v93, v201, v82
	v_cmp_lt_i32_e32 vcc, 0, v188
	v_cmp_eq_u32_e64 s[98:99], 0, v188
	v_cmp_eq_u32_e64 s[100:101], 1, v188
	s_waitcnt lgkmcnt(0)
	s_nop 1
	v_cndmask_b32_e64 v93, v93, v116, s[100:101]
	v_cndmask_b32_e64 v93, v93, v120, s[98:99]
	v_cndmask_b32_e64 v92, v92, v116, s[98:99]
	ds_bpermute_b32 v85, v204, v82
	ds_bpermute_b32 v82, v203, v82
	ds_bpermute_b32 v90, v200, v86
	ds_bpermute_b32 v91, v201, v86
	v_cmp_lt_i32_e32 vcc, 0, v188
	v_cmp_eq_u32_e64 s[98:99], 0, v188
	v_cmp_eq_u32_e64 s[100:101], 1, v188
	s_waitcnt lgkmcnt(0)
	s_nop 1
	v_cndmask_b32_e64 v91, v91, v117, s[100:101]
	v_cndmask_b32_e64 v91, v91, v121, s[98:99]
	v_cndmask_b32_e64 v90, v90, v117, s[98:99]
	s_waitcnt lgkmcnt(4)
	v_lshlrev_b32_e32 v94, 16, v93
	v_fma_f32 v94, v56, v94, v52
	v_lshlrev_b32_e32 v95, 16, v92
	v_fmac_f32_e32 v94, v48, v95
	v_fmac_f32_e32 v94, v36, v44
	v_and_b32_e32 v36, 0xffff0000, v93
	v_fma_f32 v36, v57, v36, v53
	v_and_b32_e32 v92, 0xffff0000, v92
	v_fmac_f32_e32 v36, v49, v92
	v_fmac_f32_e32 v36, v37, v45
	v_mul_f32_e32 v37, 0x3d372713, v94
	v_mul_f32_e32 v37, v94, v37
	v_mul_f32_e32 v92, 0x3d372713, v36
	v_fma_f32 v37, v94, v37, v94
	v_mul_f32_e32 v92, v36, v92
	v_mul_f32_e32 v37, 0xc0135761, v37
	v_fma_f32 v92, v36, v92, v36
	v_exp_f32_e32 v37, v37
	v_mul_f32_e32 v92, 0xc0135761, v92
	v_exp_f32_e32 v92, v92
	s_waitcnt lgkmcnt(1)
	v_and_b32_e32 v145, 0xffff0000, v90
	v_add_f32_e32 v37, 1.0, v37
	v_rcp_f32_e32 v37, v37
	v_add_f32_e32 v92, 1.0, v92
	v_rcp_f32_e32 v92, v92
	v_cmp_lt_i32_e32 vcc, 0, v188
	v_mul_f32_e32 v37, v94, v37
	v_mul_f32_e32 v37, v32, v37
	v_mul_f32_e32 v32, v36, v92
	v_lshlrev_b32_e32 v36, 16, v89
	v_fma_f32 v36, v78, v36, v62
	v_lshlrev_b32_e32 v92, 16, v88
	v_fmac_f32_e32 v36, v70, v92
	v_fmac_f32_e32 v36, v66, v74
	v_and_b32_e32 v66, 0xffff0000, v89
	v_mul_f32_e32 v89, 0x3d372713, v36
	v_mul_f32_e32 v89, v36, v89
	v_fma_f32 v89, v36, v89, v36
	v_mul_f32_e32 v89, 0xc0135761, v89
	v_exp_f32_e32 v89, v89
	v_fma_f32 v66, v79, v66, v63
	v_and_b32_e32 v88, 0xffff0000, v88
	v_fmac_f32_e32 v66, v71, v88
	v_fmac_f32_e32 v66, v67, v75
	v_add_f32_e32 v67, 1.0, v89
	v_rcp_f32_e32 v67, v67
	v_mul_f32_e32 v89, v33, v32
	v_lshlrev_b32_e32 v33, 16, v87
	v_fma_f32 v33, v76, v33, v60
	v_mul_f32_e32 v32, v36, v67
	v_mul_f32_e32 v36, v42, v32
	v_lshlrev_b32_e32 v42, 16, v47
	v_fmac_f32_e32 v33, v68, v42
	v_and_b32_e32 v42, 0xffff0000, v87
	v_fma_f32 v42, v77, v42, v61
	v_and_b32_e32 v47, 0xffff0000, v47
	v_mul_f32_e32 v88, 0x3d372713, v66
	v_fmac_f32_e32 v33, v64, v72
	v_fmac_f32_e32 v42, v69, v47
	v_mul_f32_e32 v88, v66, v88
	v_fmac_f32_e32 v42, v65, v73
	v_mul_f32_e32 v47, 0x3d372713, v33
	v_fma_f32 v88, v66, v88, v66
	v_mul_f32_e32 v47, v33, v47
	v_mul_f32_e32 v64, 0x3d372713, v42
	v_mul_f32_e32 v88, 0xc0135761, v88
	v_fma_f32 v47, v33, v47, v33
	v_mul_f32_e32 v64, v42, v64
	v_exp_f32_e32 v88, v88
	v_mul_f32_e32 v47, 0xc0135761, v47
	v_fma_f32 v64, v42, v64, v42
	v_exp_f32_e32 v47, v47
	v_mul_f32_e32 v64, 0xc0135761, v64
	v_exp_f32_e32 v64, v64
	v_add_f32_e32 v32, 1.0, v88
	v_rcp_f32_e32 v32, v32
	v_add_f32_e32 v47, 1.0, v47
	v_rcp_f32_e32 v47, v47
	v_add_f32_e32 v64, 1.0, v64
	v_rcp_f32_e32 v64, v64
	v_mul_f32_e32 v32, v66, v32
	v_mul_f32_e32 v43, v43, v32
	v_mul_f32_e32 v32, v33, v47
	v_mul_f32_e32 v40, v40, v32
	v_mul_f32_e32 v32, v42, v64
	v_mul_f32_e32 v64, v41, v32
	s_waitcnt lgkmcnt(0)
	v_and_b32_e32 v32, 0xffff0000, v91
	v_fma_f32 v42, v59, v32, v55
	v_mov_b32_e32 v32, v39
	v_mov_b32_e32 v33, v51
	v_pk_mul_f32 v[32:33], v[32:33], v[144:145]
	v_lshlrev_b32_e32 v47, 16, v90
	v_add_f32_e32 v33, v42, v33
	v_add_f32_e32 v65, v32, v33
	v_mul_f32_e32 v32, 0x3d372713, v65
	v_mul_f32_e32 v32, v65, v32
	v_fma_f32 v32, v65, v32, v65
	v_mul_f32_e32 v32, 0xc0135761, v32
	v_exp_f32_e32 v66, v32
	v_lshlrev_b32_e32 v32, 16, v91
	v_mov_b32_e32 v39, v50
	v_fma_f32 v42, v58, v32, v54
	v_pk_mul_f32 v[32:33], v[38:39], v[46:47]
	v_add_f32_e32 v38, 1.0, v66
	v_add_f32_e32 v33, v42, v33
	v_add_f32_e32 v32, v32, v33
	v_mul_f32_e32 v33, 0x3d372713, v32
	v_mul_f32_e32 v33, v32, v33
	v_fma_f32 v33, v32, v33, v32
	v_mul_f32_e32 v33, 0xc0135761, v33
	v_exp_f32_e32 v33, v33
	v_rcp_f32_e32 v38, v38
	v_add_u32_e32 v39, 0x90, v202
	ds_bpermute_b32 v41, v204, v86
	v_add_f32_e32 v33, 1.0, v33
	v_rcp_f32_e32 v33, v33
	v_mul_f32_e32 v38, v65, v38
	v_mul_f32_e32 v35, v35, v38
	ds_bpermute_b32 v42, v203, v86
	v_mul_f32_e32 v32, v32, v33
	v_mul_f32_e32 v38, v34, v32
	v_cvt_pk_bf16_f32 v32, v40, v64
	v_cvt_pk_bf16_f32 v33, v36, v43
	v_cvt_pk_bf16_f32 v34, v37, v89
	v_mov_b64_e32 v[36:37], s[14:15]
	v_mad_i64_i32 v[36:37], s[62:63], v39, s91, v[36:37]
	v_lshl_add_u64 v[36:37], v[180:181], 1, v[36:37]
	v_cvt_pk_bf16_f32 v35, v38, v35
	global_store_dwordx4 v[36:37], v[32:35], off
	s_nop 1
	v_cvt_pk_bf16_f32 v32, v28, v29
	ds_bpermute_b32 v39, v200, v32
	ds_bpermute_b32 v40, v201, v32
	v_cvt_pk_bf16_f32 v33, v30, v31
	v_cvt_pk_bf16_f32 v34, v20, v21
	v_cvt_pk_bf16_f32 v38, v22, v23
	v_cmp_eq_u32_e64 s[98:99], 0, v188
	v_cmp_eq_u32_e64 s[100:101], 1, v188
	s_waitcnt lgkmcnt(0)
; __device__ __forceinline__ unsigned cvt_pk_bf16(float lo, float hi) { unsigned r; asm volatile("v_cvt_pk_bf16_f32 %0, %1, %2" : "=v"(r) : "v"(lo), "v"(hi)); return r; }
; __device__ __forceinline__ float gelu_tanh_f(float x) { const float y = -2.3022081983651455f * (x + 0.044715f * x * x * x); return x * __builtin_amdgcn_rcpf(1.f + __builtin_amdgcn_exp2f(y)); }
;     __device__ __forceinline__ void operator()(const f32x4 (&acc)[2][2][4][2], const Unit& u, int wr, int wc, int fr, int fq) const {
;     ...
;                 for (int q = 0; q < 4; ++q) {
;                     unsigned g1 = (unsigned)__shfl_up((int)pk[q], 1, 16), g2 = (unsigned)__shfl_up((int)pk[q], 2, 16);
;                     if (fr == 0) { g1 = l15[q]; g2 = l14[q]; } else if (fr == 1) { g2 = l15[q]; }
;                     const unsigned n14 = (unsigned)__shfl((int)pk[q], 14, 16), n15 = (unsigned)__shfl((int)pk[q], 15, 16);
;                     l14[q] = n14; l15[q] = n15;
;                     const int n = q >> 1, j = (q & 1) * 2, e = 2 * q;
;                     const float x0 = bb[e] + w0[e] * __uint_as_float(g2 << 16) + w1[e] * __uint_as_float(g1 << 16) + w2[e] * acc[ai][0][m][n][j];
;                     const float x1 = bb[e + 1] + w0[e + 1] * __uint_as_float(g2 & 0xffff0000u) + w1[e + 1] * __uint_as_float(g1 & 0xffff0000u) + w2[e + 1] * acc[ai][0][m][n][j + 1];
;                     hv[e] = gelu_tanh_f(x0) * acc[ai][1][m][n][j]; hv[e + 1] = gelu_tanh_f(x1) * acc[ai][1][m][n][j + 1];
;                 }
;                 const bool first2 = (slab == 0 && m == 0 && fr < 2);
;                 if (!first2) { u32x4 w; w.x = cvt_pk_bf16(hv[0], hv[1]); w.y = cvt_pk_bf16(hv[2], hv[3]); w.z = cvt_pk_bf16(hv[4], hv[5]); w.w = cvt_pk_bf16(hv[6], hv[7]);
;                     *(u32x4*)(H + (size_t)row * ldh + f0) = w; }
	s_nop 1
	v_cndmask_b32_e64 v40, v40, v80, s[100:101]
	v_cndmask_b32_e64 v40, v40, v83, s[98:99]
	v_cndmask_b32_e64 v39, v39, v80, s[98:99]
	ds_bpermute_b32 v35, v204, v32
	ds_bpermute_b32 v32, v203, v32
	ds_bpermute_b32 v43, v200, v33
	ds_bpermute_b32 v47, v201, v33
	v_cmp_lt_i32_e32 vcc, 0, v188
	v_cmp_eq_u32_e64 s[98:99], 0, v188
	v_cmp_eq_u32_e64 s[100:101], 1, v188
	s_waitcnt lgkmcnt(0)
	s_nop 1
	v_cndmask_b32_e64 v47, v47, v81, s[100:101]
	v_cndmask_b32_e64 v47, v47, v84, s[98:99]
	v_cndmask_b32_e64 v43, v43, v81, s[98:99]
	ds_bpermute_b32 v36, v204, v33
	ds_bpermute_b32 v33, v203, v33
	ds_bpermute_b32 v66, v200, v34
	ds_bpermute_b32 v67, v201, v34
	v_cmp_lt_i32_e32 vcc, 0, v188
	v_cmp_eq_u32_e64 s[98:99], 0, v188
	v_cmp_eq_u32_e64 s[100:101], 1, v188
	s_waitcnt lgkmcnt(0)
	s_nop 1
	v_cndmask_b32_e64 v67, v67, v82, s[100:101]
	v_cndmask_b32_e64 v67, v67, v85, s[98:99]
	v_cndmask_b32_e64 v66, v66, v82, s[98:99]
	ds_bpermute_b32 v37, v204, v34
	ds_bpermute_b32 v34, v203, v34
	ds_bpermute_b32 v64, v200, v38
	ds_bpermute_b32 v65, v201, v38
	v_cmp_lt_i32_e32 vcc, 0, v188
	v_cmp_eq_u32_e64 s[98:99], 0, v188
	v_cmp_eq_u32_e64 s[100:101], 1, v188
	s_waitcnt lgkmcnt(0)
	s_nop 1
	v_cndmask_b32_e64 v65, v65, v42, s[100:101]
	v_cndmask_b32_e64 v65, v65, v41, s[98:99]
	v_cndmask_b32_e64 v64, v64, v42, s[98:99]
	s_waitcnt lgkmcnt(4)
	v_lshlrev_b32_e32 v41, 16, v67
	v_fma_f32 v41, v56, v41, v52
	v_lshlrev_b32_e32 v42, 16, v66
	v_fmac_f32_e32 v41, v48, v42
	v_fmac_f32_e32 v41, v20, v44
	v_and_b32_e32 v20, 0xffff0000, v67
	v_fma_f32 v20, v57, v20, v53
	v_and_b32_e32 v42, 0xffff0000, v66
	v_fmac_f32_e32 v20, v49, v42
	v_fmac_f32_e32 v20, v21, v45
	v_mul_f32_e32 v21, 0x3d372713, v41
	v_mul_f32_e32 v21, v41, v21
	v_mul_f32_e32 v42, 0x3d372713, v20
	v_fma_f32 v21, v41, v21, v41
	v_mul_f32_e32 v42, v20, v42
	v_mul_f32_e32 v21, 0xc0135761, v21
	v_fma_f32 v42, v20, v42, v20
	v_exp_f32_e32 v21, v21
	v_mul_f32_e32 v42, 0xc0135761, v42
	v_exp_f32_e32 v42, v42
	s_waitcnt lgkmcnt(1)
	v_and_b32_e32 v145, 0xffff0000, v64
	v_add_f32_e32 v21, 1.0, v21
	v_rcp_f32_e32 v21, v21
	v_add_f32_e32 v42, 1.0, v42
	v_rcp_f32_e32 v42, v42
	v_cmp_lt_i32_e32 vcc, 0, v188
	v_mul_f32_e32 v21, v41, v21
	v_mul_f32_e32 v41, v16, v21
	v_mul_f32_e32 v16, v20, v42
	v_lshlrev_b32_e32 v20, 16, v47
	v_fma_f32 v20, v78, v20, v62
	v_lshlrev_b32_e32 v21, 16, v43
	v_fmac_f32_e32 v20, v70, v21
	v_fmac_f32_e32 v20, v30, v74
	v_mul_f32_e32 v30, 0x3d372713, v20
	v_mul_f32_e32 v30, v20, v30
	v_fma_f32 v30, v20, v30, v20
	v_mul_f32_e32 v30, 0xc0135761, v30
	v_exp_f32_e32 v30, v30
	v_and_b32_e32 v21, 0xffff0000, v47
	v_fma_f32 v21, v79, v21, v63
	v_and_b32_e32 v42, 0xffff0000, v43
	v_add_f32_e32 v30, 1.0, v30
	v_rcp_f32_e32 v30, v30
	v_fmac_f32_e32 v21, v71, v42
	v_fmac_f32_e32 v21, v31, v75
	v_mul_f32_e32 v31, 0x3d372713, v21
	v_mul_f32_e32 v42, v17, v16
	v_lshlrev_b32_e32 v17, 16, v40
	v_mul_f32_e32 v31, v21, v31
	v_mul_f32_e32 v16, v20, v30
	v_fma_f32 v17, v76, v17, v60
	v_lshlrev_b32_e32 v20, 16, v39
	v_fma_f32 v31, v21, v31, v21
	v_fmac_f32_e32 v17, v68, v20
	v_and_b32_e32 v20, 0xffff0000, v40
	v_mul_f32_e32 v31, 0xc0135761, v31
	v_fmac_f32_e32 v17, v28, v72
	v_fma_f32 v20, v77, v20, v61
	v_and_b32_e32 v28, 0xffff0000, v39
	v_exp_f32_e32 v31, v31
	v_fmac_f32_e32 v20, v69, v28
	v_fmac_f32_e32 v20, v29, v73
	v_mul_f32_e32 v28, 0x3d372713, v17
	v_mul_f32_e32 v28, v17, v28
	v_mul_f32_e32 v29, 0x3d372713, v20
	v_fma_f32 v28, v17, v28, v17
	v_mul_f32_e32 v29, v20, v29
	v_mul_f32_e32 v26, v26, v16
	v_add_f32_e32 v16, 1.0, v31
	v_mul_f32_e32 v28, 0xc0135761, v28
	v_fma_f32 v29, v20, v29, v20
	v_rcp_f32_e32 v16, v16
	v_exp_f32_e32 v28, v28
	v_mul_f32_e32 v29, 0xc0135761, v29
	v_exp_f32_e32 v29, v29
	v_mul_f32_e32 v16, v21, v16
	v_add_f32_e32 v21, 1.0, v28
	v_rcp_f32_e32 v21, v21
	v_add_f32_e32 v28, 1.0, v29
	v_rcp_f32_e32 v28, v28
	v_mul_f32_e32 v27, v27, v16
	v_mul_f32_e32 v16, v17, v21
	v_mul_f32_e32 v24, v24, v16
	v_mul_f32_e32 v16, v20, v28
	v_mul_f32_e32 v25, v25, v16
	s_waitcnt lgkmcnt(0)
	v_and_b32_e32 v16, 0xffff0000, v65
	v_fma_f32 v21, v59, v16, v55
	v_mov_b32_e32 v16, v23
	v_mov_b32_e32 v17, v51
	v_pk_mul_f32 v[16:17], v[16:17], v[144:145]
	v_lshlrev_b32_e32 v47, 16, v64
	v_add_f32_e32 v17, v21, v17
	v_add_f32_e32 v28, v16, v17
	v_mul_f32_e32 v16, 0x3d372713, v28
	v_mul_f32_e32 v16, v28, v16
	v_fma_f32 v16, v28, v16, v28
	v_mul_f32_e32 v16, 0xc0135761, v16
	v_exp_f32_e32 v29, v16
	v_lshlrev_b32_e32 v16, 16, v65
	v_mov_b32_e32 v23, v50
	v_fma_f32 v21, v58, v16, v54
	v_pk_mul_f32 v[16:17], v[22:23], v[46:47]
	v_add_f32_e32 v22, 1.0, v29
	v_add_f32_e32 v17, v21, v17
	v_add_f32_e32 v16, v16, v17
	v_mul_f32_e32 v17, 0x3d372713, v16
	v_mul_f32_e32 v17, v16, v17
	v_fma_f32 v17, v16, v17, v16
	v_mul_f32_e32 v17, 0xc0135761, v17
	v_exp_f32_e32 v17, v17
	v_rcp_f32_e32 v22, v22
	v_add_u32_e32 v29, 0xa0, v202
	ds_bpermute_b32 v20, v204, v38
	v_add_f32_e32 v17, 1.0, v17
	v_rcp_f32_e32 v17, v17
	v_mul_f32_e32 v22, v28, v22
	v_mul_f32_e32 v19, v19, v22
	ds_bpermute_b32 v21, v203, v38
	v_mul_f32_e32 v16, v16, v17
	v_mul_f32_e32 v22, v18, v16
	v_cvt_pk_bf16_f32 v16, v24, v25
	v_cvt_pk_bf16_f32 v17, v26, v27
	v_cvt_pk_bf16_f32 v18, v41, v42
	v_cvt_pk_bf16_f32 v19, v22, v19
	v_mov_b64_e32 v[22:23], s[14:15]
	v_mad_i64_i32 v[22:23], s[62:63], v29, s91, v[22:23]
	v_lshl_add_u64 v[22:23], v[180:181], 1, v[22:23]
	global_store_dwordx4 v[22:23], v[16:19], off
	s_nop 1
	v_cvt_pk_bf16_f32 v17, v12, v13
	ds_bpermute_b32 v16, v200, v17
	ds_bpermute_b32 v17, v201, v17
	v_cvt_pk_bf16_f32 v19, v14, v15
	v_cvt_pk_bf16_f32 v22, v4, v5
	v_cvt_pk_bf16_f32 v23, v6, v7
	v_cmp_eq_u32_e64 s[98:99], 0, v188
	v_cmp_eq_u32_e64 s[100:101], 1, v188
	s_waitcnt lgkmcnt(0)
; __device__ __forceinline__ unsigned cvt_pk_bf16(float lo, float hi) { unsigned r; asm volatile("v_cvt_pk_bf16_f32 %0, %1, %2" : "=v"(r) : "v"(lo), "v"(hi)); return r; }
; __device__ __forceinline__ float gelu_tanh_f(float x) { const float y = -2.3022081983651455f * (x + 0.044715f * x * x * x); return x * __builtin_amdgcn_rcpf(1.f + __builtin_amdgcn_exp2f(y)); }
;     __device__ __forceinline__ void operator()(const f32x4 (&acc)[2][2][4][2], const Unit& u, int wr, int wc, int fr, int fq) const {
;     ...
;                 for (int q = 0; q < 4; ++q) {
;                     unsigned g1 = (unsigned)__shfl_up((int)pk[q], 1, 16), g2 = (unsigned)__shfl_up((int)pk[q], 2, 16);
;                     if (fr == 0) { g1 = l15[q]; g2 = l14[q]; } else if (fr == 1) { g2 = l15[q]; }
;                     const unsigned n14 = (unsigned)__shfl((int)pk[q], 14, 16), n15 = (unsigned)__shfl((int)pk[q], 15, 16);
;                     l14[q] = n14; l15[q] = n15;
;                     const int n = q >> 1, j = (q & 1) * 2, e = 2 * q;
;                     const float x0 = bb[e] + w0[e] * __uint_as_float(g2 << 16) + w1[e] * __uint_as_float(g1 << 16) + w2[e] * acc[ai][0][m][n][j];
;                     const float x1 = bb[e + 1] + w0[e + 1] * __uint_as_float(g2 & 0xffff0000u) + w1[e + 1] * __uint_as_float(g1 & 0xffff0000u) + w2[e + 1] * acc[ai][0][m][n][j + 1];
;                     hv[e] = gelu_tanh_f(x0) * acc[ai][1][m][n][j]; hv[e + 1] = gelu_tanh_f(x1) * acc[ai][1][m][n][j + 1];
;                 }
;                 const bool first2 = (slab == 0 && m == 0 && fr < 2);
;                 if (!first2) { u32x4 w; w.x = cvt_pk_bf16(hv[0], hv[1]); w.y = cvt_pk_bf16(hv[2], hv[3]); w.z = cvt_pk_bf16(hv[4], hv[5]); w.w = cvt_pk_bf16(hv[6], hv[7]);
;                     *(u32x4*)(H + (size_t)row * ldh + f0) = w; }
;                 else { float* p = hp + (size_t)fr * ff; *(f32x4*)p = acc[0][0][0][0]; *(f32x4*)(p + 4) = acc[0][0][0][1];
;                     float* pu = hp + (size_t)(4 + fr) * ff; *(f32x4*)pu = acc[0][1][0][0]; *(f32x4*)(pu + 4) = acc[0][1][0][1]; }
;                 if (slab == 3 && m == 3 && fr >= 14) { float* p = hp + (size_t)(2 + fr - 14) * ff; *(f32x4*)p = acc[1][0][3][0]; *(f32x4*)(p + 4) = acc[1][0][3][1]; }
	s_nop 1
	v_cndmask_b32_e64 v17, v17, v32, s[100:101]
	v_cndmask_b32_e64 v17, v17, v35, s[98:99]
	v_cndmask_b32_e64 v16, v16, v32, s[98:99]
	ds_bpermute_b32 v18, v200, v19
	ds_bpermute_b32 v19, v201, v19
	v_cmp_lt_i32_e32 vcc, 0, v188
	v_cmp_eq_u32_e64 s[98:99], 0, v188
	v_cmp_eq_u32_e64 s[100:101], 1, v188
	s_waitcnt lgkmcnt(0)
	s_nop 1
	v_cndmask_b32_e64 v19, v19, v33, s[100:101]
	v_cndmask_b32_e64 v19, v19, v36, s[98:99]
	v_cndmask_b32_e64 v18, v18, v33, s[98:99]
	ds_bpermute_b32 v24, v200, v22
	ds_bpermute_b32 v25, v201, v22
	v_cmp_lt_i32_e32 vcc, 0, v188
	v_cmp_eq_u32_e64 s[98:99], 0, v188
	v_cmp_eq_u32_e64 s[100:101], 1, v188
	s_waitcnt lgkmcnt(0)
	s_nop 1
	v_cndmask_b32_e64 v25, v25, v34, s[100:101]
	v_cndmask_b32_e64 v25, v25, v37, s[98:99]
	v_cndmask_b32_e64 v24, v24, v34, s[98:99]
	ds_bpermute_b32 v22, v200, v23
	ds_bpermute_b32 v23, v201, v23
	v_cmp_lt_i32_e32 vcc, 0, v188
	v_cmp_eq_u32_e64 s[98:99], 0, v188
	v_cmp_eq_u32_e64 s[100:101], 1, v188
	s_waitcnt lgkmcnt(0)
	s_nop 1
	v_cndmask_b32_e64 v23, v23, v21, s[100:101]
	v_cndmask_b32_e64 v23, v23, v20, s[98:99]
	v_cndmask_b32_e64 v22, v22, v21, s[98:99]
	s_waitcnt lgkmcnt(2)
	v_lshlrev_b32_e32 v20, 16, v25
	v_fma_f32 v20, v56, v20, v52
	v_lshlrev_b32_e32 v21, 16, v24
	v_fmac_f32_e32 v20, v48, v21
	v_and_b32_e32 v21, 0xffff0000, v25
	v_fma_f32 v21, v57, v21, v53
	v_and_b32_e32 v24, 0xffff0000, v24
	v_fmac_f32_e32 v20, v4, v44
	v_fmac_f32_e32 v21, v49, v24
	v_fmac_f32_e32 v21, v5, v45
	v_mul_f32_e32 v24, 0x3d372713, v20
	v_mul_f32_e32 v24, v20, v24
	v_mul_f32_e32 v25, 0x3d372713, v21
	v_fma_f32 v24, v20, v24, v20
	v_mul_f32_e32 v25, v21, v25
	v_mul_f32_e32 v24, 0xc0135761, v24
	v_fma_f32 v25, v21, v25, v21
	v_exp_f32_e32 v24, v24
	v_mul_f32_e32 v25, 0xc0135761, v25
	v_exp_f32_e32 v25, v25
	s_waitcnt lgkmcnt(1)
	v_and_b32_e32 v145, 0xffff0000, v22
	v_add_f32_e32 v24, 1.0, v24
	v_rcp_f32_e32 v24, v24
	v_add_f32_e32 v25, 1.0, v25
	v_rcp_f32_e32 v25, v25
	v_lshlrev_b32_e32 v47, 16, v22
	v_mul_f32_e32 v20, v20, v24
	v_mul_f32_e32 v20, v0, v20
	v_mul_f32_e32 v0, v21, v25
	v_lshlrev_b32_e32 v21, 16, v19
	v_fma_f32 v21, v78, v21, v62
	v_lshlrev_b32_e32 v24, 16, v18
	v_fmac_f32_e32 v21, v70, v24
	v_fmac_f32_e32 v21, v14, v74
	v_mul_f32_e32 v24, 0x3d372713, v21
	v_mul_f32_e32 v24, v21, v24
	v_fma_f32 v24, v21, v24, v21
	v_mul_f32_e32 v24, 0xc0135761, v24
	v_exp_f32_e32 v24, v24
	v_and_b32_e32 v19, 0xffff0000, v19
	v_fma_f32 v19, v79, v19, v63
	v_and_b32_e32 v18, 0xffff0000, v18
	v_fmac_f32_e32 v19, v71, v18
	v_add_f32_e32 v18, 1.0, v24
	v_rcp_f32_e32 v18, v18
	v_mul_f32_e32 v25, v1, v0
	v_lshlrev_b32_e32 v1, 16, v17
	v_fma_f32 v1, v76, v1, v60
	v_mul_f32_e32 v0, v21, v18
	v_lshlrev_b32_e32 v18, 16, v16
	v_fmac_f32_e32 v19, v15, v75
	v_fmac_f32_e32 v1, v68, v18
	v_and_b32_e32 v17, 0xffff0000, v17
	v_mul_f32_e32 v24, 0x3d372713, v19
	v_fmac_f32_e32 v1, v12, v72
	v_fmac_f32_e32 v61, v77, v17
	v_and_b32_e32 v16, 0xffff0000, v16
	v_mul_f32_e32 v24, v19, v24
	v_fmac_f32_e32 v61, v69, v16
	v_mul_f32_e32 v16, 0x3d372713, v1
	v_fma_f32 v24, v19, v24, v19
	v_fmac_f32_e32 v61, v13, v73
	v_mul_f32_e32 v16, v1, v16
	v_mul_f32_e32 v24, 0xc0135761, v24
	v_fma_f32 v16, v1, v16, v1
	v_mul_f32_e32 v17, 0x3d372713, v61
	v_exp_f32_e32 v24, v24
	v_mul_f32_e32 v16, 0xc0135761, v16
	v_mul_f32_e32 v17, v61, v17
	v_exp_f32_e32 v16, v16
	v_fma_f32 v17, v61, v17, v61
	v_mul_f32_e32 v17, 0xc0135761, v17
	v_exp_f32_e32 v17, v17
	v_mul_f32_e32 v10, v10, v0
	v_add_f32_e32 v0, 1.0, v24
	v_rcp_f32_e32 v0, v0
	v_add_f32_e32 v16, 1.0, v16
	v_rcp_f32_e32 v16, v16
	v_add_f32_e32 v17, 1.0, v17
	v_rcp_f32_e32 v17, v17
	v_mul_f32_e32 v0, v19, v0
	v_mul_f32_e32 v11, v11, v0
	v_mul_f32_e32 v0, v1, v16
	v_mul_f32_e32 v8, v8, v0
	s_waitcnt lgkmcnt(0)
	v_and_b32_e32 v0, 0xffff0000, v23
	v_mul_f32_e32 v16, v61, v17
	v_fma_f32 v17, v59, v0, v55
	v_mov_b32_e32 v0, v7
	v_mov_b32_e32 v1, v51
	v_pk_mul_f32 v[0:1], v[0:1], v[144:145]
	v_mul_f32_e32 v9, v9, v16
	v_add_f32_e32 v1, v17, v1
	v_add_f32_e32 v17, v0, v1
	v_mul_f32_e32 v0, 0x3d372713, v17
	v_mul_f32_e32 v0, v17, v0
	v_fma_f32 v0, v17, v0, v17
	v_mul_f32_e32 v0, 0xc0135761, v0
	v_exp_f32_e32 v18, v0
	v_lshlrev_b32_e32 v0, 16, v23
	v_fmac_f32_e32 v54, v58, v0
	v_mov_b32_e32 v0, v6
	v_mov_b32_e32 v1, v50
	v_pk_mul_f32 v[0:1], v[0:1], v[46:47]
	v_add_f32_e32 v16, 1.0, v18
	v_add_f32_e32 v1, v54, v1
	v_add_f32_e32 v0, v0, v1
	v_mul_f32_e32 v1, 0x3d372713, v0
	v_mul_f32_e32 v1, v0, v1
	v_fma_f32 v1, v0, v1, v0
	v_mul_f32_e32 v1, 0xc0135761, v1
	v_exp_f32_e32 v1, v1
	v_rcp_f32_e32 v16, v16
	v_add_u32_e32 v18, 0xb0, v202
	v_add_f32_e32 v1, 1.0, v1
	v_rcp_f32_e32 v1, v1
	v_mul_f32_e32 v16, v17, v16
	v_mul_f32_e32 v3, v3, v16
	v_mul_f32_e32 v0, v0, v1
	v_mul_f32_e32 v16, v2, v0
	v_cvt_pk_bf16_f32 v0, v8, v9
	v_mov_b64_e32 v[8:9], s[14:15]
	v_mad_i64_i32 v[8:9], s[62:63], v18, s91, v[8:9]
	v_lshl_add_u64 v[8:9], v[180:181], 1, v[8:9]
	v_cvt_pk_bf16_f32 v1, v10, v11
	v_cvt_pk_bf16_f32 v2, v20, v25
	v_cvt_pk_bf16_f32 v3, v16, v3
	global_store_dwordx4 v[8:9], v[0:3], off
	s_and_saveexec_b64 s[62:63], s[46:47]
	s_cbranch_execz .LBB0_1401
	global_store_dwordx4 v[112:113], v[12:15], off
	global_store_dwordx4 v[112:113], v[4:7], off offset:16

; __device__ __forceinline__ unsigned cvt_pk_bf16(float lo, float hi) { unsigned r; asm volatile("v_cvt_pk_bf16_f32 %0, %1, %2" : "=v"(r) : "v"(lo), "v"(hi)); return r; }
; __device__ __forceinline__ float gelu_tanh_f(float x) { const float y = -2.3022081983651455f * (x + 0.044715f * x * x * x); return x * __builtin_amdgcn_rcpf(1.f + __builtin_amdgcn_exp2f(y)); }
;     __device__ __forceinline__ void operator()(const f32x4 (&acc)[2][2][4][2], const Unit& u, int wr, int wc, int fr, int fq) const {
;     ...
;                 for (int q = 0; q < 4; ++q) {
;                     unsigned g1 = (unsigned)__shfl_up((int)pk[q], 1, 16), g2 = (unsigned)__shfl_up((int)pk[q], 2, 16);
;                     if (fr == 0) { g1 = l15[q]; g2 = l14[q]; } else if (fr == 1) { g2 = l15[q]; }
;                     const unsigned n14 = (unsigned)__shfl((int)pk[q], 14, 16), n15 = (unsigned)__shfl((int)pk[q], 15, 16);
;                     l14[q] = n14; l15[q] = n15;
;                     const int n = q >> 1, j = (q & 1) * 2, e = 2 * q;
;                     const float x0 = bb[e] + w0[e] * __uint_as_float(g2 << 16) + w1[e] * __uint_as_float(g1 << 16) + w2[e] * acc[ai][0][m][n][j];
;                     const float x1 = bb[e + 1] + w0[e + 1] * __uint_as_float(g2 & 0xffff0000u) + w1[e + 1] * __uint_as_float(g1 & 0xffff0000u) + w2[e + 1] * acc[ai][0][m][n][j + 1];
;                     hv[e] = gelu_tanh_f(x0) * acc[ai][1][m][n][j]; hv[e + 1] = gelu_tanh_f(x1) * acc[ai][1][m][n][j + 1];
;                 }
;                 const bool first2 = (slab == 0 && m == 0 && fr < 2);
;                 if (!first2) { u32x4 w; w.x = cvt_pk_bf16(hv[0], hv[1]); w.y = cvt_pk_bf16(hv[2], hv[3]); w.z = cvt_pk_bf16(hv[4], hv[5]); w.w = cvt_pk_bf16(hv[6], hv[7]);
;                     *(u32x4*)(H + (size_t)row * ldh + f0) = w; }
.LBB0_2407:
	v_add_u32_e32 v182, -1, v199
	v_and_b32_e32 v183, 0x70, v199
	v_cmp_lt_i32_e32 vcc, v182, v183
	v_cvt_pk_bf16_f32 v204, v104, v105
	v_cvt_pk_bf16_f32 v211, v106, v107
	v_cvt_pk_bf16_f32 v208, v100, v101
	v_cvt_pk_bf16_f32 v187, v102, v103
	s_nop 1
	v_cndmask_b32_e32 v182, v182, v199, vcc
	v_lshlrev_b32_e32 v200, 2, v182
	v_add_u32_e32 v182, -2, v199
	v_cmp_lt_i32_e32 vcc, v182, v183
	s_nop 1
	v_cndmask_b32_e32 v182, v182, v199, vcc
	v_lshlrev_b32_e32 v201, 2, v182
	ds_bpermute_b32 v182, v200, v204
	ds_bpermute_b32 v183, v201, v204
	v_cmp_lt_i32_e32 vcc, 0, v188
	v_cmp_eq_u32_e64 s[98:99], 0, v188
	v_cmp_eq_u32_e64 s[100:101], 1, v188
	s_waitcnt lgkmcnt(0)
	s_nop 1
	v_cndmask_b32_e64 v183, v183, v203, s[100:101]
	v_cndmask_b32_e64 v183, v183, v186, s[98:99]
	v_cndmask_b32_e64 v182, v182, v203, s[98:99]
	v_lshlrev_b32_e32 v186, 2, v199
	v_and_b32_e32 v212, 0x1c0, v186
	v_or_b32_e32 v203, 60, v186
	ds_bpermute_b32 v209, v212, v204 offset:56
	ds_bpermute_b32 v205, v203, v204
	ds_bpermute_b32 v186, v200, v211
	ds_bpermute_b32 v213, v201, v211
	v_or_b32_e32 v204, 56, v212
	v_cmp_lt_i32_e32 vcc, 0, v188
	v_cmp_eq_u32_e64 s[98:99], 0, v188
	v_cmp_eq_u32_e64 s[100:101], 1, v188
	s_waitcnt lgkmcnt(0)
	s_nop 1
	v_cndmask_b32_e64 v213, v213, v210, s[100:101]
	v_cndmask_b32_e64 v213, v213, v206, s[98:99]
	v_cndmask_b32_e64 v186, v186, v210, s[98:99]
	ds_bpermute_b32 v210, v204, v211
	ds_bpermute_b32 v206, v203, v211
	ds_bpermute_b32 v216, v200, v208
	ds_bpermute_b32 v217, v201, v208
	v_cmp_lt_i32_e32 vcc, 0, v188
	v_cmp_eq_u32_e64 s[98:99], 0, v188
	v_cmp_eq_u32_e64 s[100:101], 1, v188
	s_waitcnt lgkmcnt(0)
	s_nop 1
	v_cndmask_b32_e64 v217, v217, v207, s[100:101]
	v_cndmask_b32_e64 v217, v217, v202, s[98:99]
	v_cndmask_b32_e64 v216, v216, v207, s[98:99]
	ds_bpermute_b32 v211, v204, v208
	ds_bpermute_b32 v207, v203, v208
	ds_bpermute_b32 v214, v200, v187
	ds_bpermute_b32 v215, v201, v187
	v_cmp_lt_i32_e32 vcc, 0, v188
	v_cmp_eq_u32_e64 s[98:99], 0, v188
	v_cmp_eq_u32_e64 s[100:101], 1, v188
	s_waitcnt lgkmcnt(0)
	s_nop 1
	v_cndmask_b32_e64 v215, v215, v185, s[100:101]
	v_cndmask_b32_e64 v215, v215, v184, s[98:99]
	v_cndmask_b32_e64 v214, v214, v185, s[98:99]
	ds_bpermute_b32 v212, v204, v187
	ds_bpermute_b32 v208, v203, v187
	s_mul_i32 s57, s62, 0x40800
	s_mul_hi_i32 s55, s62, 0x40800
	s_add_u32 s64, s80, s57
	s_addc_u32 s65, s81, s55
	v_lshl_add_u32 v202, s62, 8, v189
	s_and_saveexec_b64 s[62:63], s[26:27]
	s_xor_b64 s[62:63], exec, s[62:63]
	s_cbranch_execz .LBB0_2433
	s_waitcnt lgkmcnt(0)
	v_lshlrev_b32_e32 v184, 16, v217
	s_waitcnt vmcnt(0)
	v_fma_f32 v184, v56, v184, v52
	v_lshlrev_b32_e32 v185, 16, v216
	v_fmac_f32_e32 v184, v48, v185
	v_fmac_f32_e32 v184, v100, v44
	v_mul_f32_e32 v187, 0x3d372713, v184
	v_mul_f32_e32 v187, v184, v187
	v_and_b32_e32 v185, 0xffff0000, v217
	v_fma_f32 v187, v184, v187, v184
	v_fma_f32 v185, v57, v185, v53
	v_mul_f32_e32 v187, 0xc0135761, v187
	v_and_b32_e32 v216, 0xffff0000, v216
	v_exp_f32_e32 v187, v187
	v_fmac_f32_e32 v185, v49, v216
	v_fmac_f32_e32 v185, v101, v45
	v_mul_f32_e32 v216, 0x3d372713, v185
	v_mul_f32_e32 v216, v185, v216
	v_add_f32_e32 v187, 1.0, v187
	v_fma_f32 v216, v185, v216, v185
	v_rcp_f32_e32 v187, v187
	v_mul_f32_e32 v216, 0xc0135761, v216
	v_exp_f32_e32 v216, v216
	v_lshlrev_b32_e32 v217, 16, v186
	v_mul_f32_e32 v184, v184, v187
	v_mul_f32_e32 v187, v88, v184
	v_add_f32_e32 v184, 1.0, v216
	v_lshlrev_b32_e32 v216, 16, v213
	v_fma_f32 v216, v78, v216, v62
	v_and_b32_e32 v213, 0xffff0000, v213
	v_fmac_f32_e32 v216, v70, v217
	v_fma_f32 v213, v79, v213, v63
	v_and_b32_e32 v186, 0xffff0000, v186
	v_fmac_f32_e32 v216, v106, v74
	v_fmac_f32_e32 v213, v71, v186
	v_fmac_f32_e32 v213, v107, v75
	v_mul_f32_e32 v186, 0x3d372713, v216
	v_mul_f32_e32 v186, v216, v186
	v_mul_f32_e32 v217, 0x3d372713, v213
	v_fma_f32 v186, v216, v186, v216
	v_mul_f32_e32 v217, v213, v217
	v_mul_f32_e32 v186, 0xc0135761, v186
	v_fma_f32 v217, v213, v217, v213
	v_rcp_f32_e32 v184, v184
	v_exp_f32_e32 v186, v186
	v_mul_f32_e32 v217, 0xc0135761, v217
	v_exp_f32_e32 v217, v217
	v_mul_f32_e32 v184, v185, v184
	v_add_f32_e32 v185, 1.0, v186
	v_rcp_f32_e32 v185, v185
	v_add_f32_e32 v186, 1.0, v217
	v_rcp_f32_e32 v186, v186
	v_mul_f32_e32 v217, v89, v184
	v_mul_f32_e32 v184, v216, v185
	v_lshlrev_b32_e32 v185, 16, v183
	v_mul_f32_e32 v216, v94, v184
	v_mul_f32_e32 v184, v213, v186
	v_fma_f32 v185, v76, v185, v60
	v_lshlrev_b32_e32 v186, 16, v182
	v_fmac_f32_e32 v185, v68, v186
	v_fmac_f32_e32 v185, v104, v72
	v_and_b32_e32 v183, 0xffff0000, v183
	v_fma_f32 v186, v77, v183, v61
	v_mul_f32_e32 v183, 0x3d372713, v185
	v_mul_f32_e32 v183, v185, v183
	v_fma_f32 v183, v185, v183, v185
	v_mul_f32_e32 v183, 0xc0135761, v183
	v_exp_f32_e32 v183, v183
	v_and_b32_e32 v182, 0xffff0000, v182
	v_fmac_f32_e32 v186, v69, v182
	v_fmac_f32_e32 v186, v105, v73
	v_add_f32_e32 v182, 1.0, v183
	v_mul_f32_e32 v183, 0x3d372713, v186
	v_mul_f32_e32 v183, v186, v183
	v_fma_f32 v183, v186, v183, v186
	v_rcp_f32_e32 v182, v182
	v_mul_f32_e32 v183, 0xc0135761, v183
	v_exp_f32_e32 v183, v183
	v_mul_f32_e32 v213, v95, v184
	v_mul_f32_e32 v182, v185, v182
	v_mul_f32_e32 v218, v92, v182
	v_add_f32_e32 v182, 1.0, v183
	v_rcp_f32_e32 v219, v182
	v_and_b32_e32 v182, 0xffff0000, v215
	v_fma_f32 v220, v59, v182, v55
	v_and_b32_e32 v183, 0xffff0000, v214
	v_mov_b32_e32 v184, v103
	v_mov_b32_e32 v185, v51
	v_mov_b32_e32 v182, v47
	v_pk_mul_f32 v[182:183], v[184:185], v[182:183]
	v_mov_b32_e32 v184, v102
	v_add_f32_e32 v183, v220, v183
	v_add_f32_e32 v220, v182, v183
	v_mul_f32_e32 v182, 0x3d372713, v220
	v_mul_f32_e32 v182, v220, v182
	v_fma_f32 v182, v220, v182, v220
	v_mul_f32_e32 v182, 0xc0135761, v182
	v_exp_f32_e32 v221, v182
	v_lshlrev_b32_e32 v182, 16, v215
	v_fma_f32 v215, v58, v182, v54
	v_lshlrev_b32_e32 v183, 16, v214
	v_mov_b32_e32 v185, v50
	v_mov_b32_e32 v182, v46
	v_pk_mul_f32 v[182:183], v[184:185], v[182:183]
	v_add_f32_e32 v185, 1.0, v221
	v_add_f32_e32 v183, v215, v183
	v_add_f32_e32 v182, v182, v183
	v_mul_f32_e32 v183, 0x3d372713, v182
	v_mul_f32_e32 v183, v182, v183
	v_fma_f32 v183, v182, v183, v182
	v_mul_f32_e32 v183, 0xc0135761, v183
	v_exp_f32_e32 v183, v183
	v_rcp_f32_e32 v185, v185
	v_mul_f32_e32 v184, v186, v219
	v_mul_f32_e32 v184, v93, v184
	v_add_f32_e32 v183, 1.0, v183
	v_rcp_f32_e32 v183, v183
	v_mul_f32_e32 v185, v220, v185
	v_mul_f32_e32 v185, v91, v185
	v_mul_f32_e32 v182, v182, v183
	v_mul_f32_e32 v186, v90, v182
	v_cvt_pk_bf16_f32 v182, v218, v184
	v_cvt_pk_bf16_f32 v183, v216, v213
	v_cvt_pk_bf16_f32 v184, v187, v217
	v_cvt_pk_bf16_f32 v185, v186, v185
	v_mov_b64_e32 v[186:187], s[14:15]
	v_mad_i64_i32 v[186:187], s[66:67], v202, s91, v[186:187]
	v_lshl_add_u64 v[186:187], v[180:181], 1, v[186:187]
	global_store_dwordx4 v[186:187], v[182:185], off

; __device__ __forceinline__ unsigned cvt_pk_bf16(float lo, float hi) { unsigned r; asm volatile("v_cvt_pk_bf16_f32 %0, %1, %2" : "=v"(r) : "v"(lo), "v"(hi)); return r; }
; __device__ __forceinline__ float gelu_tanh_f(float x) { const float y = -2.3022081983651455f * (x + 0.044715f * x * x * x); return x * __builtin_amdgcn_rcpf(1.f + __builtin_amdgcn_exp2f(y)); }
;     __device__ __forceinline__ void operator()(const f32x4 (&acc)[2][2][4][2], const Unit& u, int wr, int wc, int fr, int fq) const {
;     ...
;                 for (int q = 0; q < 4; ++q) {
;                     unsigned g1 = (unsigned)__shfl_up((int)pk[q], 1, 16), g2 = (unsigned)__shfl_up((int)pk[q], 2, 16);
;                     if (fr == 0) { g1 = l15[q]; g2 = l14[q]; } else if (fr == 1) { g2 = l15[q]; }
;                     const unsigned n14 = (unsigned)__shfl((int)pk[q], 14, 16), n15 = (unsigned)__shfl((int)pk[q], 15, 16);
;                     l14[q] = n14; l15[q] = n15;
;                     const int n = q >> 1, j = (q & 1) * 2, e = 2 * q;
;                     const float x0 = bb[e] + w0[e] * __uint_as_float(g2 << 16) + w1[e] * __uint_as_float(g1 << 16) + w2[e] * acc[ai][0][m][n][j];
;                     const float x1 = bb[e + 1] + w0[e + 1] * __uint_as_float(g2 & 0xffff0000u) + w1[e + 1] * __uint_as_float(g1 & 0xffff0000u) + w2[e + 1] * acc[ai][0][m][n][j + 1];
;                     hv[e] = gelu_tanh_f(x0) * acc[ai][1][m][n][j]; hv[e + 1] = gelu_tanh_f(x1) * acc[ai][1][m][n][j + 1];
;                 }
;                 const bool first2 = (slab == 0 && m == 0 && fr < 2);
;                 if (!first2) { u32x4 w; w.x = cvt_pk_bf16(hv[0], hv[1]); w.y = cvt_pk_bf16(hv[2], hv[3]); w.z = cvt_pk_bf16(hv[4], hv[5]); w.w = cvt_pk_bf16(hv[6], hv[7]);
;                     *(u32x4*)(H + (size_t)row * ldh + f0) = w; }
.LBB0_2435:
	s_or_b64 exec, exec, s[62:63]
	v_cvt_pk_bf16_f32 v216, v156, v157
	ds_bpermute_b32 v214, v200, v216
	ds_bpermute_b32 v215, v201, v216
	v_cmp_lt_i32_e32 vcc, 0, v188
	v_cvt_pk_bf16_f32 v219, v158, v159
	v_cvt_pk_bf16_f32 v218, v148, v149
	v_cvt_pk_bf16_f32 v213, v150, v151
	v_cmp_eq_u32_e64 s[98:99], 0, v188
	v_cmp_eq_u32_e64 s[100:101], 1, v188
	s_waitcnt lgkmcnt(0)
	s_nop 1
	v_cndmask_b32_e64 v215, v215, v205, s[100:101]
	v_cndmask_b32_e64 v215, v215, v209, s[98:99]
	v_cndmask_b32_e64 v214, v214, v205, s[98:99]
	ds_bpermute_b32 v209, v204, v216
	ds_bpermute_b32 v205, v203, v216
	ds_bpermute_b32 v216, v200, v219
	ds_bpermute_b32 v217, v201, v219
	v_cmp_lt_i32_e32 vcc, 0, v188
	v_cmp_eq_u32_e64 s[98:99], 0, v188
	v_cmp_eq_u32_e64 s[100:101], 1, v188
	s_waitcnt lgkmcnt(0)
	s_nop 1
	v_cndmask_b32_e64 v217, v217, v206, s[100:101]
	v_cndmask_b32_e64 v217, v217, v210, s[98:99]
	v_cndmask_b32_e64 v216, v216, v206, s[98:99]
	ds_bpermute_b32 v210, v204, v219
	ds_bpermute_b32 v206, v203, v219
	ds_bpermute_b32 v220, v200, v218
	ds_bpermute_b32 v221, v201, v218
	v_cmp_lt_i32_e32 vcc, 0, v188
	v_cmp_eq_u32_e64 s[98:99], 0, v188
	v_cmp_eq_u32_e64 s[100:101], 1, v188
	s_waitcnt lgkmcnt(0)
	s_nop 1
	v_cndmask_b32_e64 v221, v221, v207, s[100:101]
	v_cndmask_b32_e64 v221, v221, v211, s[98:99]
	v_cndmask_b32_e64 v220, v220, v207, s[98:99]
	ds_bpermute_b32 v211, v204, v218
	ds_bpermute_b32 v207, v203, v218
	ds_bpermute_b32 v218, v200, v213
	ds_bpermute_b32 v219, v201, v213
	v_cmp_lt_i32_e32 vcc, 0, v188
	v_cmp_eq_u32_e64 s[98:99], 0, v188
	v_cmp_eq_u32_e64 s[100:101], 1, v188
	s_waitcnt lgkmcnt(0)
	s_nop 1
	v_cndmask_b32_e64 v219, v219, v208, s[100:101]
	v_cndmask_b32_e64 v219, v219, v212, s[98:99]
	v_cndmask_b32_e64 v218, v218, v208, s[98:99]
	s_waitcnt lgkmcnt(0)
	v_lshlrev_b32_e32 v208, 16, v221
	s_waitcnt vmcnt(0)
	v_fma_f32 v208, v56, v208, v52
	v_lshlrev_b32_e32 v212, 16, v220
	v_fmac_f32_e32 v208, v48, v212
	v_fmac_f32_e32 v208, v148, v44
	v_and_b32_e32 v148, 0xffff0000, v221
	v_fma_f32 v148, v57, v148, v53
	v_and_b32_e32 v212, 0xffff0000, v220
	v_fmac_f32_e32 v148, v49, v212
	v_fmac_f32_e32 v148, v149, v45
	v_mul_f32_e32 v149, 0x3d372713, v208
	v_mul_f32_e32 v149, v208, v149
	v_mul_f32_e32 v212, 0x3d372713, v148
	v_fma_f32 v149, v208, v149, v208
	v_mul_f32_e32 v212, v148, v212
	v_mul_f32_e32 v149, 0xc0135761, v149
	v_fma_f32 v212, v148, v212, v148
	v_exp_f32_e32 v149, v149
	v_mul_f32_e32 v212, 0xc0135761, v212
	v_exp_f32_e32 v212, v212
	v_cmp_lt_i32_e32 vcc, 0, v188
	v_add_f32_e32 v149, 1.0, v149
	v_rcp_f32_e32 v149, v149
	v_add_f32_e32 v212, 1.0, v212
	v_rcp_f32_e32 v212, v212
	v_mul_f32_e32 v149, v208, v149
	v_mul_f32_e32 v208, v144, v149
	v_mul_f32_e32 v144, v148, v212
	v_lshlrev_b32_e32 v148, 16, v217
	v_fma_f32 v148, v78, v148, v62
	v_lshlrev_b32_e32 v149, 16, v216
	v_fmac_f32_e32 v148, v70, v149
	v_fmac_f32_e32 v148, v158, v74
	v_mul_f32_e32 v158, 0x3d372713, v148
	v_mul_f32_e32 v158, v148, v158
	v_fma_f32 v158, v148, v158, v148
	v_mul_f32_e32 v158, 0xc0135761, v158
	v_exp_f32_e32 v158, v158
	v_and_b32_e32 v149, 0xffff0000, v217
	v_fma_f32 v149, v79, v149, v63
	v_and_b32_e32 v212, 0xffff0000, v216
	v_add_f32_e32 v158, 1.0, v158
	v_rcp_f32_e32 v158, v158
	v_fmac_f32_e32 v149, v71, v212
	v_fmac_f32_e32 v149, v159, v75
	v_mul_f32_e32 v159, 0x3d372713, v149
	v_mul_f32_e32 v145, v145, v144
	v_mul_f32_e32 v144, v148, v158
	v_lshlrev_b32_e32 v148, 16, v215
	v_mul_f32_e32 v159, v149, v159
	v_mul_f32_e32 v158, v154, v144
	v_fma_f32 v148, v76, v148, v60
	v_lshlrev_b32_e32 v154, 16, v214
	v_fma_f32 v159, v149, v159, v149
	v_fmac_f32_e32 v148, v68, v154
	v_and_b32_e32 v154, 0xffff0000, v215
	v_mul_f32_e32 v159, 0xc0135761, v159
	v_fmac_f32_e32 v148, v156, v72
	v_fma_f32 v154, v77, v154, v61
	v_and_b32_e32 v156, 0xffff0000, v214
	v_exp_f32_e32 v159, v159
	v_fmac_f32_e32 v154, v69, v156
	v_fmac_f32_e32 v154, v157, v73
	v_mul_f32_e32 v156, 0x3d372713, v148
	v_mul_f32_e32 v156, v148, v156
	v_mul_f32_e32 v157, 0x3d372713, v154
	v_fma_f32 v156, v148, v156, v148
	v_mul_f32_e32 v157, v154, v157
	v_add_f32_e32 v144, 1.0, v159
	v_mul_f32_e32 v156, 0xc0135761, v156
	v_fma_f32 v157, v154, v157, v154
	v_rcp_f32_e32 v144, v144
	v_exp_f32_e32 v156, v156
	v_mul_f32_e32 v157, 0xc0135761, v157
	v_exp_f32_e32 v157, v157
	v_mul_f32_e32 v144, v149, v144
	v_add_f32_e32 v149, 1.0, v156
	v_rcp_f32_e32 v149, v149
	v_add_f32_e32 v156, 1.0, v157
	v_rcp_f32_e32 v156, v156
	v_mul_f32_e32 v157, v155, v144
	v_mul_f32_e32 v144, v148, v149
	v_mul_f32_e32 v152, v152, v144
	v_mul_f32_e32 v144, v154, v156
	v_mul_f32_e32 v156, v153, v144
	v_and_b32_e32 v144, 0xffff0000, v219
	v_and_b32_e32 v149, 0xffff0000, v218
	v_mov_b32_e32 v154, v151
	v_mov_b32_e32 v155, v51
	v_mov_b32_e32 v148, v47
	v_fma_f32 v159, v59, v144, v55
	v_pk_mul_f32 v[148:149], v[154:155], v[148:149]
	v_mov_b32_e32 v144, v47
	v_add_f32_e32 v47, v159, v149
	v_add_f32_e32 v155, v148, v47
	v_mul_f32_e32 v47, 0x3d372713, v155
	v_mul_f32_e32 v47, v155, v47
	v_fma_f32 v47, v155, v47, v155
	v_mul_f32_e32 v47, 0xc0135761, v47
	v_exp_f32_e32 v159, v47
	v_lshlrev_b32_e32 v47, 16, v219
	v_fma_f32 v154, v58, v47, v54
	v_lshlrev_b32_e32 v47, 16, v218
	v_mov_b32_e32 v151, v50
	v_pk_mul_f32 v[148:149], v[150:151], v[46:47]
	v_mov_b64_e32 v[150:151], s[14:15]
	v_add_f32_e32 v47, v154, v149
	v_add_f32_e32 v47, v148, v47
	v_mul_f32_e32 v148, 0x3d372713, v47
	v_mul_f32_e32 v148, v47, v148
	v_fma_f32 v148, v47, v148, v47
	v_mul_f32_e32 v148, 0xc0135761, v148
	v_exp_f32_e32 v148, v148
	v_add_f32_e32 v149, 1.0, v159
	v_rcp_f32_e32 v149, v149
	v_or_b32_e32 v159, 16, v202
	v_add_f32_e32 v148, 1.0, v148
	v_rcp_f32_e32 v148, v148
	v_mul_f32_e32 v149, v155, v149
	v_mad_i64_i32 v[150:151], s[62:63], v159, s91, v[150:151]
	v_mul_f32_e32 v47, v47, v148
	v_mul_f32_e32 v149, v147, v149
	v_mul_f32_e32 v47, v146, v47
	v_cvt_pk_bf16_f32 v146, v152, v156
	v_lshl_add_u64 v[150:151], v[180:181], 1, v[150:151]
	ds_bpermute_b32 v153, v204, v213
	ds_bpermute_b32 v154, v203, v213
	v_cvt_pk_bf16_f32 v147, v158, v157
	v_cvt_pk_bf16_f32 v148, v208, v145
	v_cvt_pk_bf16_f32 v149, v47, v149
	global_store_dwordx4 v[150:151], v[146:149], off
	s_nop 1
	v_cvt_pk_bf16_f32 v146, v140, v141
	ds_bpermute_b32 v47, v200, v146
	ds_bpermute_b32 v145, v201, v146
	v_cvt_pk_bf16_f32 v147, v142, v143
	v_cvt_pk_bf16_f32 v148, v132, v133
	v_cvt_pk_bf16_f32 v152, v134, v135
	v_cmp_eq_u32_e64 s[98:99], 0, v188
	v_cmp_eq_u32_e64 s[100:101], 1, v188
	s_waitcnt lgkmcnt(0)
; __device__ __forceinline__ unsigned cvt_pk_bf16(float lo, float hi) { unsigned r; asm volatile("v_cvt_pk_bf16_f32 %0, %1, %2" : "=v"(r) : "v"(lo), "v"(hi)); return r; }
; __device__ __forceinline__ float gelu_tanh_f(float x) { const float y = -2.3022081983651455f * (x + 0.044715f * x * x * x); return x * __builtin_amdgcn_rcpf(1.f + __builtin_amdgcn_exp2f(y)); }
;     __device__ __forceinline__ void operator()(const f32x4 (&acc)[2][2][4][2], const Unit& u, int wr, int wc, int fr, int fq) const {
;     ...
;                 for (int q = 0; q < 4; ++q) {
;                     unsigned g1 = (unsigned)__shfl_up((int)pk[q], 1, 16), g2 = (unsigned)__shfl_up((int)pk[q], 2, 16);
;                     if (fr == 0) { g1 = l15[q]; g2 = l14[q]; } else if (fr == 1) { g2 = l15[q]; }
;                     const unsigned n14 = (unsigned)__shfl((int)pk[q], 14, 16), n15 = (unsigned)__shfl((int)pk[q], 15, 16);
;                     l14[q] = n14; l15[q] = n15;
;                     const int n = q >> 1, j = (q & 1) * 2, e = 2 * q;
;                     const float x0 = bb[e] + w0[e] * __uint_as_float(g2 << 16) + w1[e] * __uint_as_float(g1 << 16) + w2[e] * acc[ai][0][m][n][j];
;                     const float x1 = bb[e + 1] + w0[e + 1] * __uint_as_float(g2 & 0xffff0000u) + w1[e + 1] * __uint_as_float(g1 & 0xffff0000u) + w2[e + 1] * acc[ai][0][m][n][j + 1];
;                     hv[e] = gelu_tanh_f(x0) * acc[ai][1][m][n][j]; hv[e + 1] = gelu_tanh_f(x1) * acc[ai][1][m][n][j + 1];
;                 }
;                 const bool first2 = (slab == 0 && m == 0 && fr < 2);
;                 if (!first2) { u32x4 w; w.x = cvt_pk_bf16(hv[0], hv[1]); w.y = cvt_pk_bf16(hv[2], hv[3]); w.z = cvt_pk_bf16(hv[4], hv[5]); w.w = cvt_pk_bf16(hv[6], hv[7]);
;                     *(u32x4*)(H + (size_t)row * ldh + f0) = w; }
	s_nop 1
	v_cndmask_b32_e64 v145, v145, v205, s[100:101]
	v_cndmask_b32_e64 v145, v145, v209, s[98:99]
	v_cndmask_b32_e64 v47, v47, v205, s[98:99]
	ds_bpermute_b32 v149, v204, v146
	ds_bpermute_b32 v146, v203, v146
	ds_bpermute_b32 v155, v200, v147
	ds_bpermute_b32 v156, v201, v147
	v_cmp_lt_i32_e32 vcc, 0, v188
	v_cmp_eq_u32_e64 s[98:99], 0, v188
	v_cmp_eq_u32_e64 s[100:101], 1, v188
	s_waitcnt lgkmcnt(0)
	s_nop 1
	v_cndmask_b32_e64 v156, v156, v206, s[100:101]
	v_cndmask_b32_e64 v156, v156, v210, s[98:99]
	v_cndmask_b32_e64 v155, v155, v206, s[98:99]
	ds_bpermute_b32 v150, v204, v147
	ds_bpermute_b32 v147, v203, v147
	ds_bpermute_b32 v159, v200, v148
	ds_bpermute_b32 v205, v201, v148
	v_cmp_lt_i32_e32 vcc, 0, v188
	v_cmp_eq_u32_e64 s[98:99], 0, v188
	v_cmp_eq_u32_e64 s[100:101], 1, v188
	s_waitcnt lgkmcnt(0)
	s_nop 1
	v_cndmask_b32_e64 v205, v205, v207, s[100:101]
	v_cndmask_b32_e64 v205, v205, v211, s[98:99]
	v_cndmask_b32_e64 v159, v159, v207, s[98:99]
	ds_bpermute_b32 v151, v204, v148
	ds_bpermute_b32 v148, v203, v148
	ds_bpermute_b32 v157, v200, v152
	ds_bpermute_b32 v158, v201, v152
	v_cmp_lt_i32_e32 vcc, 0, v188
	v_cmp_eq_u32_e64 s[98:99], 0, v188
	v_cmp_eq_u32_e64 s[100:101], 1, v188
	s_waitcnt lgkmcnt(0)
	s_nop 1
	v_cndmask_b32_e64 v158, v158, v154, s[100:101]
	v_cndmask_b32_e64 v158, v158, v153, s[98:99]
	v_cndmask_b32_e64 v157, v157, v154, s[98:99]
	s_waitcnt lgkmcnt(4)
	v_lshlrev_b32_e32 v153, 16, v205
	v_fma_f32 v153, v56, v153, v52
	v_lshlrev_b32_e32 v154, 16, v159
	v_fmac_f32_e32 v153, v48, v154
	v_fmac_f32_e32 v153, v132, v44
	v_and_b32_e32 v132, 0xffff0000, v205
	v_fma_f32 v132, v57, v132, v53
	v_and_b32_e32 v154, 0xffff0000, v159
	v_fmac_f32_e32 v132, v49, v154
	v_fmac_f32_e32 v132, v133, v45
	v_mul_f32_e32 v133, 0x3d372713, v153
	v_mul_f32_e32 v133, v153, v133
	v_fma_f32 v133, v153, v133, v153
	v_mul_f32_e32 v133, 0xc0135761, v133
	v_exp_f32_e32 v133, v133
	v_mul_f32_e32 v154, 0x3d372713, v132
	v_mul_f32_e32 v154, v132, v154
	v_fma_f32 v154, v132, v154, v132
	v_add_f32_e32 v133, 1.0, v133
	v_rcp_f32_e32 v133, v133
	v_mul_f32_e32 v154, 0xc0135761, v154
	v_exp_f32_e32 v154, v154
	v_cmp_lt_i32_e32 vcc, 0, v188
	v_mul_f32_e32 v133, v153, v133
	v_mul_f32_e32 v128, v128, v133
	v_lshlrev_b32_e32 v133, 16, v156
	v_fma_f32 v133, v78, v133, v62
	v_lshlrev_b32_e32 v153, 16, v155
	v_fmac_f32_e32 v133, v70, v153
	v_fmac_f32_e32 v133, v142, v74
	v_mul_f32_e32 v153, 0x3d372713, v133
	v_add_f32_e32 v154, 1.0, v154
	v_mul_f32_e32 v153, v133, v153
	v_rcp_f32_e32 v154, v154
	v_fma_f32 v153, v133, v153, v133
	v_mul_f32_e32 v153, 0xc0135761, v153
	v_exp_f32_e32 v153, v153
	v_and_b32_e32 v142, 0xffff0000, v156
	v_mul_f32_e32 v132, v132, v154
	v_fma_f32 v142, v79, v142, v63
	v_and_b32_e32 v154, 0xffff0000, v155
	v_fmac_f32_e32 v142, v71, v154
	v_fmac_f32_e32 v142, v143, v75
	v_add_f32_e32 v143, 1.0, v153
	v_rcp_f32_e32 v143, v143
	v_mul_f32_e32 v154, v129, v132
	v_lshlrev_b32_e32 v132, 16, v145
	v_fma_f32 v132, v76, v132, v60
	v_mul_f32_e32 v129, v133, v143
	v_lshlrev_b32_e32 v133, 16, v47
	v_fmac_f32_e32 v132, v68, v133
	v_and_b32_e32 v133, 0xffff0000, v145
	v_fma_f32 v133, v77, v133, v61
	v_and_b32_e32 v47, 0xffff0000, v47
	v_fmac_f32_e32 v132, v140, v72
	v_fmac_f32_e32 v133, v69, v47
	v_fmac_f32_e32 v133, v141, v73
	v_mul_f32_e32 v47, 0x3d372713, v132
	v_mul_f32_e32 v47, v132, v47
	v_mul_f32_e32 v140, 0x3d372713, v133
	v_fma_f32 v47, v132, v47, v132
	v_mul_f32_e32 v140, v133, v140
	v_mul_f32_e32 v47, 0xc0135761, v47
	v_fma_f32 v140, v133, v140, v133
	v_exp_f32_e32 v47, v47
	v_mul_f32_e32 v140, 0xc0135761, v140
	v_exp_f32_e32 v140, v140
	v_mul_f32_e32 v153, 0x3d372713, v142
	v_add_f32_e32 v47, 1.0, v47
	v_rcp_f32_e32 v47, v47
	v_add_f32_e32 v140, 1.0, v140
	v_rcp_f32_e32 v140, v140
	v_mul_f32_e32 v153, v142, v153
	v_fma_f32 v153, v142, v153, v142
	v_mul_f32_e32 v47, v132, v47
	v_mul_f32_e32 v153, 0xc0135761, v153
	v_mul_f32_e32 v136, v136, v47
	v_mul_f32_e32 v47, v133, v140
	v_exp_f32_e32 v153, v153
	v_mul_f32_e32 v137, v137, v47
	s_waitcnt lgkmcnt(0)
	v_and_b32_e32 v47, 0xffff0000, v158
	v_and_b32_e32 v145, 0xffff0000, v157
	v_mov_b32_e32 v132, v135
	v_mov_b32_e32 v133, v51
	v_fma_f32 v47, v59, v47, v55
	v_pk_mul_f32 v[132:133], v[132:133], v[144:145]
	v_mul_f32_e32 v138, v138, v129
	v_add_f32_e32 v47, v47, v133
	v_add_f32_e32 v140, v132, v47
	v_add_f32_e32 v129, 1.0, v153
	v_mul_f32_e32 v47, 0x3d372713, v140
	v_rcp_f32_e32 v129, v129
	v_mul_f32_e32 v47, v140, v47
	v_fma_f32 v47, v140, v47, v140
	v_mul_f32_e32 v47, 0xc0135761, v47
	v_exp_f32_e32 v141, v47
	v_lshlrev_b32_e32 v47, 16, v158
	v_mul_f32_e32 v129, v142, v129
	v_fma_f32 v142, v58, v47, v54
	v_lshlrev_b32_e32 v47, 16, v157
	v_mov_b32_e32 v135, v50
	v_pk_mul_f32 v[132:133], v[134:135], v[46:47]
	v_add_f32_e32 v134, 1.0, v141
	v_add_f32_e32 v47, v142, v133
	v_add_f32_e32 v47, v132, v47
	v_mul_f32_e32 v132, 0x3d372713, v47
	v_mul_f32_e32 v132, v47, v132
	v_fma_f32 v132, v47, v132, v47
	v_mul_f32_e32 v132, 0xc0135761, v132
	v_exp_f32_e32 v133, v132
	v_rcp_f32_e32 v134, v134
	v_mul_f32_e32 v139, v139, v129
	v_or_b32_e32 v141, 32, v202
	v_add_f32_e32 v133, 1.0, v133
	v_rcp_f32_e32 v133, v133
	v_mul_f32_e32 v134, v140, v134
	v_mul_f32_e32 v131, v131, v134
	v_cvt_pk_bf16_f32 v134, v136, v137
	v_mul_f32_e32 v47, v47, v133
	v_mul_f32_e32 v47, v130, v47
	v_cvt_pk_bf16_f32 v135, v138, v139
	v_cvt_pk_bf16_f32 v136, v128, v154
	v_cvt_pk_bf16_f32 v137, v47, v131
	v_mov_b64_e32 v[130:131], s[14:15]
	v_mad_i64_i32 v[130:131], s[62:63], v141, s91, v[130:131]
	v_lshl_add_u64 v[130:131], v[180:181], 1, v[130:131]
	global_store_dwordx4 v[130:131], v[134:137], off
	v_cvt_pk_bf16_f32 v128, v124, v125
	ds_bpermute_b32 v129, v204, v152
	ds_bpermute_b32 v132, v203, v152
	ds_bpermute_b32 v47, v200, v128
	ds_bpermute_b32 v128, v201, v128
	v_cvt_pk_bf16_f32 v131, v126, v127
	v_cvt_pk_bf16_f32 v133, v120, v121
	v_cvt_pk_bf16_f32 v134, v122, v123
	v_cmp_eq_u32_e64 s[98:99], 0, v188
	v_cmp_eq_u32_e64 s[100:101], 1, v188
	s_waitcnt lgkmcnt(0)
; __device__ __forceinline__ unsigned cvt_pk_bf16(float lo, float hi) { unsigned r; asm volatile("v_cvt_pk_bf16_f32 %0, %1, %2" : "=v"(r) : "v"(lo), "v"(hi)); return r; }
; __device__ __forceinline__ float gelu_tanh_f(float x) { const float y = -2.3022081983651455f * (x + 0.044715f * x * x * x); return x * __builtin_amdgcn_rcpf(1.f + __builtin_amdgcn_exp2f(y)); }
;     __device__ __forceinline__ void operator()(const f32x4 (&acc)[2][2][4][2], const Unit& u, int wr, int wc, int fr, int fq) const {
;     ...
;                 for (int q = 0; q < 4; ++q) {
;                     unsigned g1 = (unsigned)__shfl_up((int)pk[q], 1, 16), g2 = (unsigned)__shfl_up((int)pk[q], 2, 16);
;                     if (fr == 0) { g1 = l15[q]; g2 = l14[q]; } else if (fr == 1) { g2 = l15[q]; }
;                     const unsigned n14 = (unsigned)__shfl((int)pk[q], 14, 16), n15 = (unsigned)__shfl((int)pk[q], 15, 16);
;                     l14[q] = n14; l15[q] = n15;
;                     const int n = q >> 1, j = (q & 1) * 2, e = 2 * q;
;                     const float x0 = bb[e] + w0[e] * __uint_as_float(g2 << 16) + w1[e] * __uint_as_float(g1 << 16) + w2[e] * acc[ai][0][m][n][j];
;                     const float x1 = bb[e + 1] + w0[e + 1] * __uint_as_float(g2 & 0xffff0000u) + w1[e + 1] * __uint_as_float(g1 & 0xffff0000u) + w2[e + 1] * acc[ai][0][m][n][j + 1];
;                     hv[e] = gelu_tanh_f(x0) * acc[ai][1][m][n][j]; hv[e + 1] = gelu_tanh_f(x1) * acc[ai][1][m][n][j + 1];
;                 }
;                 const bool first2 = (slab == 0 && m == 0 && fr < 2);
;                 if (!first2) { u32x4 w; w.x = cvt_pk_bf16(hv[0], hv[1]); w.y = cvt_pk_bf16(hv[2], hv[3]); w.z = cvt_pk_bf16(hv[4], hv[5]); w.w = cvt_pk_bf16(hv[6], hv[7]);
;                     *(u32x4*)(H + (size_t)row * ldh + f0) = w; }
;                 else { float* p = hp + (size_t)fr * ff; *(f32x4*)p = acc[0][0][0][0]; *(f32x4*)(p + 4) = acc[0][0][0][1];
;                     float* pu = hp + (size_t)(4 + fr) * ff; *(f32x4*)pu = acc[0][1][0][0]; *(f32x4*)(pu + 4) = acc[0][1][0][1]; }
	s_nop 1
	v_cndmask_b32_e64 v128, v128, v146, s[100:101]
	v_cndmask_b32_e64 v128, v128, v149, s[98:99]
	v_cndmask_b32_e64 v47, v47, v146, s[98:99]
	ds_bpermute_b32 v130, v200, v131
	ds_bpermute_b32 v131, v201, v131
	v_cmp_lt_i32_e32 vcc, 0, v188
	v_cmp_eq_u32_e64 s[98:99], 0, v188
	v_cmp_eq_u32_e64 s[100:101], 1, v188
	s_waitcnt lgkmcnt(0)
	s_nop 1
	v_cndmask_b32_e64 v131, v131, v147, s[100:101]
	v_cndmask_b32_e64 v131, v131, v150, s[98:99]
	v_cndmask_b32_e64 v130, v130, v147, s[98:99]
	ds_bpermute_b32 v135, v200, v133
	ds_bpermute_b32 v136, v201, v133
	v_cmp_lt_i32_e32 vcc, 0, v188
	v_cmp_eq_u32_e64 s[98:99], 0, v188
	v_cmp_eq_u32_e64 s[100:101], 1, v188
	s_waitcnt lgkmcnt(0)
	s_nop 1
	v_cndmask_b32_e64 v136, v136, v148, s[100:101]
	v_cndmask_b32_e64 v136, v136, v151, s[98:99]
	v_cndmask_b32_e64 v135, v135, v148, s[98:99]
	ds_bpermute_b32 v133, v200, v134
	ds_bpermute_b32 v134, v201, v134
	v_cmp_lt_i32_e32 vcc, 0, v188
	v_cmp_eq_u32_e64 s[98:99], 0, v188
	v_cmp_eq_u32_e64 s[100:101], 1, v188
	s_waitcnt lgkmcnt(0)
	s_nop 1
	v_cndmask_b32_e64 v134, v134, v132, s[100:101]
	v_cndmask_b32_e64 v134, v134, v129, s[98:99]
	v_cndmask_b32_e64 v133, v133, v132, s[98:99]
	s_waitcnt lgkmcnt(2)
	v_lshlrev_b32_e32 v129, 16, v136
	v_fma_f32 v129, v56, v129, v52
	v_lshlrev_b32_e32 v132, 16, v135
	v_fmac_f32_e32 v129, v48, v132
	v_fmac_f32_e32 v129, v120, v44
	v_and_b32_e32 v120, 0xffff0000, v136
	v_fma_f32 v120, v57, v120, v53
	v_and_b32_e32 v132, 0xffff0000, v135
	v_fmac_f32_e32 v120, v49, v132
	v_fmac_f32_e32 v120, v121, v45
	v_mul_f32_e32 v121, 0x3d372713, v129
	v_mul_f32_e32 v121, v129, v121
	v_mul_f32_e32 v132, 0x3d372713, v120
	v_fma_f32 v121, v129, v121, v129
	v_mul_f32_e32 v132, v120, v132
	v_mul_f32_e32 v121, 0xc0135761, v121
	v_fma_f32 v132, v120, v132, v120
	v_exp_f32_e32 v121, v121
	v_mul_f32_e32 v132, 0xc0135761, v132
	v_exp_f32_e32 v132, v132
	s_waitcnt lgkmcnt(1)
	v_and_b32_e32 v145, 0xffff0000, v133
	v_add_f32_e32 v121, 1.0, v121
	v_rcp_f32_e32 v121, v121
	v_add_f32_e32 v132, 1.0, v132
	v_rcp_f32_e32 v132, v132
	v_mul_f32_e32 v121, v129, v121
	v_mul_f32_e32 v121, v112, v121
	v_mul_f32_e32 v112, v120, v132
	v_lshlrev_b32_e32 v120, 16, v131
	v_fma_f32 v120, v78, v120, v62
	v_lshlrev_b32_e32 v129, 16, v130
	v_fmac_f32_e32 v120, v70, v129
	v_fmac_f32_e32 v120, v126, v74
	v_mul_f32_e32 v129, 0x3d372713, v120
	v_mul_f32_e32 v129, v120, v129
	v_fma_f32 v129, v120, v129, v120
	v_mul_f32_e32 v129, 0xc0135761, v129
	v_exp_f32_e32 v129, v129
	v_and_b32_e32 v126, 0xffff0000, v131
	v_fma_f32 v126, v79, v126, v63
	v_and_b32_e32 v130, 0xffff0000, v130
	v_fmac_f32_e32 v126, v71, v130
	v_fmac_f32_e32 v126, v127, v75
	v_add_f32_e32 v127, 1.0, v129
	v_rcp_f32_e32 v127, v127
	v_mul_f32_e32 v130, v113, v112
	v_lshlrev_b32_e32 v113, 16, v128
	v_fma_f32 v113, v76, v113, v60
	v_mul_f32_e32 v112, v120, v127
	v_lshlrev_b32_e32 v120, 16, v47
	v_fmac_f32_e32 v113, v68, v120
	v_and_b32_e32 v120, 0xffff0000, v128
	v_fmac_f32_e32 v113, v124, v72
	v_fma_f32 v120, v77, v120, v61
	v_and_b32_e32 v47, 0xffff0000, v47
	v_mul_f32_e32 v129, 0x3d372713, v126
	v_fmac_f32_e32 v120, v69, v47
	v_mul_f32_e32 v47, 0x3d372713, v113
	v_mul_f32_e32 v129, v126, v129
	v_mul_f32_e32 v47, v113, v47
	v_fma_f32 v129, v126, v129, v126
	v_fma_f32 v47, v113, v47, v113
	v_mul_f32_e32 v129, 0xc0135761, v129
	v_fmac_f32_e32 v120, v125, v73
	v_mul_f32_e32 v47, 0xc0135761, v47
	v_exp_f32_e32 v129, v129
	v_exp_f32_e32 v47, v47
	v_mul_f32_e32 v124, 0x3d372713, v120
	v_mul_f32_e32 v124, v120, v124
	v_fma_f32 v124, v120, v124, v120
	v_mul_f32_e32 v124, 0xc0135761, v124
	v_mul_f32_e32 v118, v118, v112
	v_add_f32_e32 v112, 1.0, v129
	v_exp_f32_e32 v124, v124
	v_add_f32_e32 v47, 1.0, v47
	v_rcp_f32_e32 v112, v112
	v_rcp_f32_e32 v47, v47
	v_add_f32_e32 v124, 1.0, v124
	v_rcp_f32_e32 v124, v124
	v_mul_f32_e32 v112, v126, v112
	v_mul_f32_e32 v47, v113, v47
	v_mul_f32_e32 v119, v119, v112
	v_mul_f32_e32 v116, v116, v47
	s_waitcnt lgkmcnt(0)
	v_and_b32_e32 v47, 0xffff0000, v134
	v_mov_b32_e32 v112, v123
	v_mov_b32_e32 v113, v51
	v_fma_f32 v47, v59, v47, v55
	v_pk_mul_f32 v[112:113], v[112:113], v[144:145]
	v_mul_f32_e32 v120, v120, v124
	v_add_f32_e32 v47, v47, v113
	v_add_f32_e32 v124, v112, v47
	v_mul_f32_e32 v47, 0x3d372713, v124
	v_mul_f32_e32 v47, v124, v47
	v_fma_f32 v47, v124, v47, v124
	v_mul_f32_e32 v47, 0xc0135761, v47
	v_exp_f32_e32 v125, v47
	v_lshlrev_b32_e32 v47, 16, v134
	v_fma_f32 v126, v58, v47, v54
	v_lshlrev_b32_e32 v47, 16, v133
	v_mov_b32_e32 v123, v50
	v_pk_mul_f32 v[112:113], v[122:123], v[46:47]
	s_nop 0
	v_add_f32_e32 v47, v126, v113
	v_add_f32_e32 v47, v112, v47
	v_mul_f32_e32 v112, 0x3d372713, v47
	v_mul_f32_e32 v112, v47, v112
	v_fma_f32 v112, v47, v112, v47
	v_mul_f32_e32 v112, 0xc0135761, v112
	v_exp_f32_e32 v112, v112
	v_mul_f32_e32 v113, v117, v120
	v_add_f32_e32 v117, 1.0, v125
	v_rcp_f32_e32 v117, v117
	v_add_f32_e32 v112, 1.0, v112
	v_rcp_f32_e32 v112, v112
	v_or_b32_e32 v120, 48, v202
	v_mul_f32_e32 v117, v124, v117
	v_mul_f32_e32 v115, v115, v117
	v_mul_f32_e32 v47, v47, v112
	v_cvt_pk_bf16_f32 v112, v116, v113
	v_mov_b64_e32 v[116:117], s[14:15]
	v_mad_i64_i32 v[116:117], s[62:63], v120, s91, v[116:117]
	v_cvt_pk_bf16_f32 v113, v118, v119
	v_lshl_add_u64 v[116:117], v[180:181], 1, v[116:117]
	v_mul_f32_e32 v47, v114, v47
	v_cvt_pk_bf16_f32 v114, v121, v130
	v_cvt_pk_bf16_f32 v115, v47, v115
	global_store_dwordx4 v[116:117], v[112:115], off
	s_nop 1
	v_lshl_add_u64 v[112:113], v[186:187], 0, v[170:171]
	s_and_saveexec_b64 s[62:63], s[42:43]
	s_cbranch_execz .LBB0_2509
	global_store_dwordx4 v[112:113], v[12:15], off
	global_store_dwordx4 v[112:113], v[4:7], off offset:16

; __device__ __forceinline__ unsigned cvt_pk_bf16(float lo, float hi) { unsigned r; asm volatile("v_cvt_pk_bf16_f32 %0, %1, %2" : "=v"(r) : "v"(lo), "v"(hi)); return r; }
; __device__ __forceinline__ float gelu_tanh_f(float x) { const float y = -2.3022081983651455f * (x + 0.044715f * x * x * x); return x * __builtin_amdgcn_rcpf(1.f + __builtin_amdgcn_exp2f(y)); }
;     __device__ __forceinline__ void operator()(const f32x4 (&acc)[2][2][4][2], const Unit& u, int wr, int wc, int fr, int fq) const {
;     ...
;                 for (int q = 0; q < 4; ++q) {
;                     unsigned g1 = (unsigned)__shfl_up((int)pk[q], 1, 16), g2 = (unsigned)__shfl_up((int)pk[q], 2, 16);
;                     if (fr == 0) { g1 = l15[q]; g2 = l14[q]; } else if (fr == 1) { g2 = l15[q]; }
;                     const unsigned n14 = (unsigned)__shfl((int)pk[q], 14, 16), n15 = (unsigned)__shfl((int)pk[q], 15, 16);
;                     l14[q] = n14; l15[q] = n15;
;                     const int n = q >> 1, j = (q & 1) * 2, e = 2 * q;
;                     const float x0 = bb[e] + w0[e] * __uint_as_float(g2 << 16) + w1[e] * __uint_as_float(g1 << 16) + w2[e] * acc[ai][0][m][n][j];
;                     const float x1 = bb[e + 1] + w0[e + 1] * __uint_as_float(g2 & 0xffff0000u) + w1[e + 1] * __uint_as_float(g1 & 0xffff0000u) + w2[e + 1] * acc[ai][0][m][n][j + 1];
;                     hv[e] = gelu_tanh_f(x0) * acc[ai][1][m][n][j]; hv[e + 1] = gelu_tanh_f(x1) * acc[ai][1][m][n][j + 1];
;                 }
;                 const bool first2 = (slab == 0 && m == 0 && fr < 2);
;                 if (!first2) { u32x4 w; w.x = cvt_pk_bf16(hv[0], hv[1]); w.y = cvt_pk_bf16(hv[2], hv[3]); w.z = cvt_pk_bf16(hv[4], hv[5]); w.w = cvt_pk_bf16(hv[6], hv[7]);
;                     *(u32x4*)(H + (size_t)row * ldh + f0) = w; }
.LBB0_2511:
	v_cvt_pk_bf16_f32 v123, v108, v109
	ds_bpermute_b32 v47, v200, v123
	ds_bpermute_b32 v122, v201, v123
	v_cmp_lt_i32_e32 vcc, 0, v188
	v_cvt_pk_bf16_f32 v127, v110, v111
	v_cvt_pk_bf16_f32 v126, v96, v97
	v_cvt_pk_bf16_f32 v124, v98, v99
	v_cmp_eq_u32_e64 s[98:99], 0, v188
	v_cmp_eq_u32_e64 s[100:101], 1, v188
	s_waitcnt lgkmcnt(0)
	s_nop 1
	v_cndmask_b32_e64 v122, v122, v118, s[100:101]
	v_cndmask_b32_e64 v122, v122, v114, s[98:99]
	v_cndmask_b32_e64 v47, v47, v118, s[98:99]
	ds_bpermute_b32 v118, v204, v123
	ds_bpermute_b32 v114, v203, v123
	ds_bpermute_b32 v123, v200, v127
	ds_bpermute_b32 v125, v201, v127
	v_cmp_lt_i32_e32 vcc, 0, v188
	v_cmp_eq_u32_e64 s[98:99], 0, v188
	v_cmp_eq_u32_e64 s[100:101], 1, v188
	s_waitcnt lgkmcnt(0)
	s_nop 1
	v_cndmask_b32_e64 v125, v125, v119, s[100:101]
	v_cndmask_b32_e64 v125, v125, v115, s[98:99]
	v_cndmask_b32_e64 v123, v123, v119, s[98:99]
	ds_bpermute_b32 v119, v204, v127
	ds_bpermute_b32 v115, v203, v127
	ds_bpermute_b32 v128, v200, v126
	ds_bpermute_b32 v129, v201, v126
	v_cmp_lt_i32_e32 vcc, 0, v188
	v_cmp_eq_u32_e64 s[98:99], 0, v188
	v_cmp_eq_u32_e64 s[100:101], 1, v188
	s_waitcnt lgkmcnt(0)
	s_nop 1
	v_cndmask_b32_e64 v129, v129, v120, s[100:101]
	v_cndmask_b32_e64 v129, v129, v116, s[98:99]
	v_cndmask_b32_e64 v128, v128, v120, s[98:99]
	ds_bpermute_b32 v120, v204, v126
	ds_bpermute_b32 v116, v203, v126
	ds_bpermute_b32 v126, v200, v124
	ds_bpermute_b32 v127, v201, v124
	v_cmp_lt_i32_e32 vcc, 0, v188
	v_cmp_eq_u32_e64 s[98:99], 0, v188
	v_cmp_eq_u32_e64 s[100:101], 1, v188
	s_waitcnt lgkmcnt(0)
	s_nop 1
	v_cndmask_b32_e64 v127, v127, v121, s[100:101]
	v_cndmask_b32_e64 v127, v127, v117, s[98:99]
	v_cndmask_b32_e64 v126, v126, v121, s[98:99]
	ds_bpermute_b32 v121, v204, v124
	ds_bpermute_b32 v117, v203, v124
	s_and_saveexec_b64 s[62:63], s[46:47]
	s_xor_b64 s[62:63], exec, s[62:63]
	s_cbranch_execz .LBB0_2537
	s_waitcnt lgkmcnt(6)
	v_lshlrev_b32_e32 v124, 16, v129
	v_fma_f32 v124, v56, v124, v52
	v_lshlrev_b32_e32 v130, 16, v128
	v_fmac_f32_e32 v124, v48, v130
	v_fmac_f32_e32 v124, v96, v44
	v_and_b32_e32 v96, 0xffff0000, v129
	v_fma_f32 v96, v57, v96, v53
	v_and_b32_e32 v128, 0xffff0000, v128
	v_fmac_f32_e32 v96, v49, v128
	v_fmac_f32_e32 v96, v97, v45
	v_mul_f32_e32 v97, 0x3d372713, v124
	v_mul_f32_e32 v97, v124, v97
	v_mul_f32_e32 v128, 0x3d372713, v96
	v_fma_f32 v97, v124, v97, v124
	v_mul_f32_e32 v128, v96, v128
	v_mul_f32_e32 v97, 0xc0135761, v97
	v_fma_f32 v128, v96, v128, v96
	v_exp_f32_e32 v97, v97
	v_mul_f32_e32 v128, 0xc0135761, v128
	v_exp_f32_e32 v128, v128
	s_waitcnt lgkmcnt(3)
	v_and_b32_e32 v145, 0xffff0000, v126
	v_add_f32_e32 v97, 1.0, v97
	v_rcp_f32_e32 v97, v97
	v_add_f32_e32 v128, 1.0, v128
	v_rcp_f32_e32 v128, v128
	v_mul_f32_e32 v97, v124, v97
	v_mul_f32_e32 v97, v80, v97
	v_mul_f32_e32 v80, v96, v128
	v_lshlrev_b32_e32 v96, 16, v125
	v_fma_f32 v96, v78, v96, v62
	v_lshlrev_b32_e32 v124, 16, v123
	v_fmac_f32_e32 v96, v70, v124
	v_fmac_f32_e32 v96, v110, v74
	v_mul_f32_e32 v124, 0x3d372713, v96
	v_mul_f32_e32 v124, v96, v124
	v_fma_f32 v124, v96, v124, v96
	v_mul_f32_e32 v124, 0xc0135761, v124
	v_exp_f32_e32 v124, v124
	v_and_b32_e32 v110, 0xffff0000, v125
	v_fma_f32 v110, v79, v110, v63
	v_and_b32_e32 v123, 0xffff0000, v123
	v_fmac_f32_e32 v110, v71, v123
	v_fmac_f32_e32 v110, v111, v75
	v_add_f32_e32 v111, 1.0, v124
	v_rcp_f32_e32 v111, v111
	v_mul_f32_e32 v124, v81, v80
	v_lshlrev_b32_e32 v81, 16, v122
	v_fma_f32 v81, v76, v81, v60
	v_mul_f32_e32 v80, v96, v111
	v_lshlrev_b32_e32 v96, 16, v47
	v_fmac_f32_e32 v81, v68, v96
	v_and_b32_e32 v96, 0xffff0000, v122
	v_fmac_f32_e32 v81, v108, v72
	v_fma_f32 v96, v77, v96, v61
	v_and_b32_e32 v47, 0xffff0000, v47
	v_mul_f32_e32 v123, 0x3d372713, v110
	v_fmac_f32_e32 v96, v69, v47
	v_mul_f32_e32 v47, 0x3d372713, v81
	v_mul_f32_e32 v123, v110, v123
	v_mul_f32_e32 v47, v81, v47
	v_fma_f32 v123, v110, v123, v110
	v_fma_f32 v47, v81, v47, v81
	v_mul_f32_e32 v123, 0xc0135761, v123
	v_fmac_f32_e32 v96, v109, v73
	v_mul_f32_e32 v47, 0xc0135761, v47
	v_exp_f32_e32 v123, v123
	v_exp_f32_e32 v47, v47
	v_mul_f32_e32 v108, 0x3d372713, v96
	v_mul_f32_e32 v108, v96, v108
	v_fma_f32 v108, v96, v108, v96
	v_mul_f32_e32 v108, 0xc0135761, v108
	v_mul_f32_e32 v86, v86, v80
	v_add_f32_e32 v80, 1.0, v123
	v_exp_f32_e32 v108, v108
	v_add_f32_e32 v47, 1.0, v47
	v_rcp_f32_e32 v80, v80
	v_rcp_f32_e32 v47, v47
	v_add_f32_e32 v108, 1.0, v108
	v_rcp_f32_e32 v108, v108
	v_mul_f32_e32 v80, v110, v80
	v_mul_f32_e32 v47, v81, v47
	v_mul_f32_e32 v87, v87, v80
	v_mul_f32_e32 v84, v84, v47
	s_waitcnt lgkmcnt(2)
	v_and_b32_e32 v47, 0xffff0000, v127
	v_mov_b32_e32 v80, v99
	v_mov_b32_e32 v81, v51
	v_fma_f32 v47, v59, v47, v55
	v_pk_mul_f32 v[80:81], v[80:81], v[144:145]
	v_mul_f32_e32 v96, v96, v108
	v_add_f32_e32 v47, v47, v81
	v_add_f32_e32 v108, v80, v47
	v_mul_f32_e32 v47, 0x3d372713, v108
	v_mul_f32_e32 v47, v108, v47
	v_fma_f32 v47, v108, v47, v108
	v_mul_f32_e32 v47, 0xc0135761, v47
	v_exp_f32_e32 v109, v47
	v_lshlrev_b32_e32 v47, 16, v127
	v_fma_f32 v110, v58, v47, v54
	v_lshlrev_b32_e32 v47, 16, v126
	v_mov_b32_e32 v99, v50
	v_pk_mul_f32 v[80:81], v[98:99], v[46:47]
	s_nop 0
	v_add_f32_e32 v47, v110, v81
	v_add_f32_e32 v47, v80, v47
	v_mul_f32_e32 v80, 0x3d372713, v47
	v_mul_f32_e32 v80, v47, v80
	v_fma_f32 v80, v47, v80, v47
	v_mul_f32_e32 v80, 0xc0135761, v80
	v_exp_f32_e32 v80, v80
	v_mul_f32_e32 v81, v85, v96
	v_add_f32_e32 v85, 1.0, v109
	v_rcp_f32_e32 v85, v85
	v_add_f32_e32 v80, 1.0, v80
	v_rcp_f32_e32 v80, v80
	v_add_u32_e32 v96, 0x80, v202
	v_mul_f32_e32 v85, v108, v85
	v_mul_f32_e32 v83, v83, v85
	v_mul_f32_e32 v47, v47, v80
	v_cvt_pk_bf16_f32 v80, v84, v81
	v_mov_b64_e32 v[84:85], s[14:15]
	v_mad_i64_i32 v[84:85], s[64:65], v96, s91, v[84:85]
	v_lshl_add_u64 v[84:85], v[180:181], 1, v[84:85]
	v_mul_f32_e32 v47, v82, v47
	v_cvt_pk_bf16_f32 v81, v86, v87
	v_cvt_pk_bf16_f32 v82, v97, v124
	v_cvt_pk_bf16_f32 v83, v47, v83
	global_store_dwordx4 v[84:85], v[80:83], off

; __device__ __forceinline__ unsigned cvt_pk_bf16(float lo, float hi) { unsigned r; asm volatile("v_cvt_pk_bf16_f32 %0, %1, %2" : "=v"(r) : "v"(lo), "v"(hi)); return r; }
; __device__ __forceinline__ float gelu_tanh_f(float x) { const float y = -2.3022081983651455f * (x + 0.044715f * x * x * x); return x * __builtin_amdgcn_rcpf(1.f + __builtin_amdgcn_exp2f(y)); }
;     __device__ __forceinline__ void operator()(const f32x4 (&acc)[2][2][4][2], const Unit& u, int wr, int wc, int fr, int fq) const {
;     ...
;                 for (int q = 0; q < 4; ++q) {
;                     unsigned g1 = (unsigned)__shfl_up((int)pk[q], 1, 16), g2 = (unsigned)__shfl_up((int)pk[q], 2, 16);
;                     if (fr == 0) { g1 = l15[q]; g2 = l14[q]; } else if (fr == 1) { g2 = l15[q]; }
;                     const unsigned n14 = (unsigned)__shfl((int)pk[q], 14, 16), n15 = (unsigned)__shfl((int)pk[q], 15, 16);
;                     l14[q] = n14; l15[q] = n15;
;                     const int n = q >> 1, j = (q & 1) * 2, e = 2 * q;
;                     const float x0 = bb[e] + w0[e] * __uint_as_float(g2 << 16) + w1[e] * __uint_as_float(g1 << 16) + w2[e] * acc[ai][0][m][n][j];
;                     const float x1 = bb[e + 1] + w0[e + 1] * __uint_as_float(g2 & 0xffff0000u) + w1[e + 1] * __uint_as_float(g1 & 0xffff0000u) + w2[e + 1] * acc[ai][0][m][n][j + 1];
;                     hv[e] = gelu_tanh_f(x0) * acc[ai][1][m][n][j]; hv[e + 1] = gelu_tanh_f(x1) * acc[ai][1][m][n][j + 1];
;                 }
;                 const bool first2 = (slab == 0 && m == 0 && fr < 2);
;                 if (!first2) { u32x4 w; w.x = cvt_pk_bf16(hv[0], hv[1]); w.y = cvt_pk_bf16(hv[2], hv[3]); w.z = cvt_pk_bf16(hv[4], hv[5]); w.w = cvt_pk_bf16(hv[6], hv[7]);
;                     *(u32x4*)(H + (size_t)row * ldh + f0) = w; }
.LBB0_2539:
	s_or_b64 exec, exec, s[62:63]
	v_cvt_pk_bf16_f32 v80, v64, v65
	s_waitcnt lgkmcnt(14)
	ds_bpermute_b32 v47, v200, v80
	ds_bpermute_b32 v87, v201, v80
	v_cmp_lt_i32_e32 vcc, 0, v188
	v_cvt_pk_bf16_f32 v81, v66, v67
	v_cvt_pk_bf16_f32 v82, v36, v37
	v_cvt_pk_bf16_f32 v86, v38, v39
	v_cmp_eq_u32_e64 s[98:99], 0, v188
	v_cmp_eq_u32_e64 s[100:101], 1, v188
	s_waitcnt lgkmcnt(0)
	s_nop 1
	v_cndmask_b32_e64 v87, v87, v114, s[100:101]
	v_cndmask_b32_e64 v87, v87, v118, s[98:99]
	v_cndmask_b32_e64 v47, v47, v114, s[98:99]
	ds_bpermute_b32 v83, v204, v80
	ds_bpermute_b32 v80, v203, v80
	ds_bpermute_b32 v88, v200, v81
	ds_bpermute_b32 v89, v201, v81
	v_cmp_lt_i32_e32 vcc, 0, v188
	v_cmp_eq_u32_e64 s[98:99], 0, v188
	v_cmp_eq_u32_e64 s[100:101], 1, v188
	s_waitcnt lgkmcnt(0)
	s_nop 1
	v_cndmask_b32_e64 v89, v89, v115, s[100:101]
	v_cndmask_b32_e64 v89, v89, v119, s[98:99]
	v_cndmask_b32_e64 v88, v88, v115, s[98:99]
	ds_bpermute_b32 v84, v204, v81
	ds_bpermute_b32 v81, v203, v81
	ds_bpermute_b32 v92, v200, v82
	ds_bpermute_b32 v93, v201, v82
	v_cmp_lt_i32_e32 vcc, 0, v188
	v_cmp_eq_u32_e64 s[98:99], 0, v188
	v_cmp_eq_u32_e64 s[100:101], 1, v188
	s_waitcnt lgkmcnt(0)
	s_nop 1
	v_cndmask_b32_e64 v93, v93, v116, s[100:101]
	v_cndmask_b32_e64 v93, v93, v120, s[98:99]
	v_cndmask_b32_e64 v92, v92, v116, s[98:99]
	ds_bpermute_b32 v85, v204, v82
	ds_bpermute_b32 v82, v203, v82
	ds_bpermute_b32 v90, v200, v86
	ds_bpermute_b32 v91, v201, v86
	v_cmp_lt_i32_e32 vcc, 0, v188
	v_cmp_eq_u32_e64 s[98:99], 0, v188
	v_cmp_eq_u32_e64 s[100:101], 1, v188
	s_waitcnt lgkmcnt(0)
	s_nop 1
	v_cndmask_b32_e64 v91, v91, v117, s[100:101]
	v_cndmask_b32_e64 v91, v91, v121, s[98:99]
	v_cndmask_b32_e64 v90, v90, v117, s[98:99]
	s_waitcnt lgkmcnt(4)
	v_lshlrev_b32_e32 v94, 16, v93
	v_fma_f32 v94, v56, v94, v52
	v_lshlrev_b32_e32 v95, 16, v92
	v_fmac_f32_e32 v94, v48, v95
	v_fmac_f32_e32 v94, v36, v44
	v_and_b32_e32 v36, 0xffff0000, v93
	v_fma_f32 v36, v57, v36, v53
	v_and_b32_e32 v92, 0xffff0000, v92
	v_fmac_f32_e32 v36, v49, v92
	v_fmac_f32_e32 v36, v37, v45
	v_mul_f32_e32 v37, 0x3d372713, v94
	v_mul_f32_e32 v37, v94, v37
	v_mul_f32_e32 v92, 0x3d372713, v36
	v_fma_f32 v37, v94, v37, v94
	v_mul_f32_e32 v92, v36, v92
	v_mul_f32_e32 v37, 0xc0135761, v37
	v_fma_f32 v92, v36, v92, v36
	v_exp_f32_e32 v37, v37
	v_mul_f32_e32 v92, 0xc0135761, v92
	v_exp_f32_e32 v92, v92
	s_waitcnt lgkmcnt(1)
	v_and_b32_e32 v145, 0xffff0000, v90
	v_add_f32_e32 v37, 1.0, v37
	v_rcp_f32_e32 v37, v37
	v_add_f32_e32 v92, 1.0, v92
	v_rcp_f32_e32 v92, v92
	v_cmp_lt_i32_e32 vcc, 0, v188
	v_mul_f32_e32 v37, v94, v37
	v_mul_f32_e32 v37, v32, v37
	v_mul_f32_e32 v32, v36, v92
	v_lshlrev_b32_e32 v36, 16, v89
	v_fma_f32 v36, v78, v36, v62
	v_lshlrev_b32_e32 v92, 16, v88
	v_fmac_f32_e32 v36, v70, v92
	v_fmac_f32_e32 v36, v66, v74
	v_and_b32_e32 v66, 0xffff0000, v89
	v_mul_f32_e32 v89, 0x3d372713, v36
	v_mul_f32_e32 v89, v36, v89
	v_fma_f32 v89, v36, v89, v36
	v_mul_f32_e32 v89, 0xc0135761, v89
	v_exp_f32_e32 v89, v89
	v_fma_f32 v66, v79, v66, v63
	v_and_b32_e32 v88, 0xffff0000, v88
	v_fmac_f32_e32 v66, v71, v88
	v_fmac_f32_e32 v66, v67, v75
	v_add_f32_e32 v67, 1.0, v89
	v_rcp_f32_e32 v67, v67
	v_mul_f32_e32 v89, v33, v32
	v_lshlrev_b32_e32 v33, 16, v87
	v_fma_f32 v33, v76, v33, v60
	v_mul_f32_e32 v32, v36, v67
	v_mul_f32_e32 v36, v42, v32
	v_lshlrev_b32_e32 v42, 16, v47
	v_fmac_f32_e32 v33, v68, v42
	v_and_b32_e32 v42, 0xffff0000, v87
	v_fma_f32 v42, v77, v42, v61
	v_and_b32_e32 v47, 0xffff0000, v47
	v_mul_f32_e32 v88, 0x3d372713, v66
	v_fmac_f32_e32 v33, v64, v72
	v_fmac_f32_e32 v42, v69, v47
	v_mul_f32_e32 v88, v66, v88
	v_fmac_f32_e32 v42, v65, v73
	v_mul_f32_e32 v47, 0x3d372713, v33
	v_fma_f32 v88, v66, v88, v66
	v_mul_f32_e32 v47, v33, v47
	v_mul_f32_e32 v64, 0x3d372713, v42
	v_mul_f32_e32 v88, 0xc0135761, v88
	v_fma_f32 v47, v33, v47, v33
	v_mul_f32_e32 v64, v42, v64
	v_exp_f32_e32 v88, v88
	v_mul_f32_e32 v47, 0xc0135761, v47
	v_fma_f32 v64, v42, v64, v42
	v_exp_f32_e32 v47, v47
	v_mul_f32_e32 v64, 0xc0135761, v64
	v_exp_f32_e32 v64, v64
	v_add_f32_e32 v32, 1.0, v88
	v_rcp_f32_e32 v32, v32
	v_add_f32_e32 v47, 1.0, v47
	v_rcp_f32_e32 v47, v47
	v_add_f32_e32 v64, 1.0, v64
	v_rcp_f32_e32 v64, v64
	v_mul_f32_e32 v32, v66, v32
	v_mul_f32_e32 v43, v43, v32
	v_mul_f32_e32 v32, v33, v47
	v_mul_f32_e32 v40, v40, v32
	v_mul_f32_e32 v32, v42, v64
	v_mul_f32_e32 v64, v41, v32
	s_waitcnt lgkmcnt(0)
	v_and_b32_e32 v32, 0xffff0000, v91
	v_fma_f32 v42, v59, v32, v55
	v_mov_b32_e32 v32, v39
	v_mov_b32_e32 v33, v51
	v_pk_mul_f32 v[32:33], v[32:33], v[144:145]
	v_lshlrev_b32_e32 v47, 16, v90
	v_add_f32_e32 v33, v42, v33
	v_add_f32_e32 v65, v32, v33
	v_mul_f32_e32 v32, 0x3d372713, v65
	v_mul_f32_e32 v32, v65, v32
	v_fma_f32 v32, v65, v32, v65
	v_mul_f32_e32 v32, 0xc0135761, v32
	v_exp_f32_e32 v66, v32
	v_lshlrev_b32_e32 v32, 16, v91
	v_mov_b32_e32 v39, v50
	v_fma_f32 v42, v58, v32, v54
	v_pk_mul_f32 v[32:33], v[38:39], v[46:47]
	v_add_f32_e32 v38, 1.0, v66
	v_add_f32_e32 v33, v42, v33
	v_add_f32_e32 v32, v32, v33
	v_mul_f32_e32 v33, 0x3d372713, v32
	v_mul_f32_e32 v33, v32, v33
	v_fma_f32 v33, v32, v33, v32
	v_mul_f32_e32 v33, 0xc0135761, v33
	v_exp_f32_e32 v33, v33
	v_rcp_f32_e32 v38, v38
	v_add_u32_e32 v39, 0x90, v202
	ds_bpermute_b32 v41, v204, v86
	v_add_f32_e32 v33, 1.0, v33
	v_rcp_f32_e32 v33, v33
	v_mul_f32_e32 v38, v65, v38
	v_mul_f32_e32 v35, v35, v38
	ds_bpermute_b32 v42, v203, v86
	v_mul_f32_e32 v32, v32, v33
	v_mul_f32_e32 v38, v34, v32
	v_cvt_pk_bf16_f32 v32, v40, v64
	v_cvt_pk_bf16_f32 v33, v36, v43
	v_cvt_pk_bf16_f32 v34, v37, v89
	v_mov_b64_e32 v[36:37], s[14:15]
	v_mad_i64_i32 v[36:37], s[62:63], v39, s91, v[36:37]
	v_lshl_add_u64 v[36:37], v[180:181], 1, v[36:37]
	v_cvt_pk_bf16_f32 v35, v38, v35
	global_store_dwordx4 v[36:37], v[32:35], off
	s_nop 1
	v_cvt_pk_bf16_f32 v32, v28, v29
	ds_bpermute_b32 v39, v200, v32
	ds_bpermute_b32 v40, v201, v32
	v_cvt_pk_bf16_f32 v33, v30, v31
	v_cvt_pk_bf16_f32 v34, v20, v21
	v_cvt_pk_bf16_f32 v38, v22, v23
	v_cmp_eq_u32_e64 s[98:99], 0, v188
	v_cmp_eq_u32_e64 s[100:101], 1, v188
	s_waitcnt lgkmcnt(0)
; __device__ __forceinline__ unsigned cvt_pk_bf16(float lo, float hi) { unsigned r; asm volatile("v_cvt_pk_bf16_f32 %0, %1, %2" : "=v"(r) : "v"(lo), "v"(hi)); return r; }
; __device__ __forceinline__ float gelu_tanh_f(float x) { const float y = -2.3022081983651455f * (x + 0.044715f * x * x * x); return x * __builtin_amdgcn_rcpf(1.f + __builtin_amdgcn_exp2f(y)); }
;     __device__ __forceinline__ void operator()(const f32x4 (&acc)[2][2][4][2], const Unit& u, int wr, int wc, int fr, int fq) const {
;     ...
;                 for (int q = 0; q < 4; ++q) {
;                     unsigned g1 = (unsigned)__shfl_up((int)pk[q], 1, 16), g2 = (unsigned)__shfl_up((int)pk[q], 2, 16);
;                     if (fr == 0) { g1 = l15[q]; g2 = l14[q]; } else if (fr == 1) { g2 = l15[q]; }
;                     const unsigned n14 = (unsigned)__shfl((int)pk[q], 14, 16), n15 = (unsigned)__shfl((int)pk[q], 15, 16);
;                     l14[q] = n14; l15[q] = n15;
;                     const int n = q >> 1, j = (q & 1) * 2, e = 2 * q;
;                     const float x0 = bb[e] + w0[e] * __uint_as_float(g2 << 16) + w1[e] * __uint_as_float(g1 << 16) + w2[e] * acc[ai][0][m][n][j];
;                     const float x1 = bb[e + 1] + w0[e + 1] * __uint_as_float(g2 & 0xffff0000u) + w1[e + 1] * __uint_as_float(g1 & 0xffff0000u) + w2[e + 1] * acc[ai][0][m][n][j + 1];
;                     hv[e] = gelu_tanh_f(x0) * acc[ai][1][m][n][j]; hv[e + 1] = gelu_tanh_f(x1) * acc[ai][1][m][n][j + 1];
;                 }
;                 const bool first2 = (slab == 0 && m == 0 && fr < 2);
;                 if (!first2) { u32x4 w; w.x = cvt_pk_bf16(hv[0], hv[1]); w.y = cvt_pk_bf16(hv[2], hv[3]); w.z = cvt_pk_bf16(hv[4], hv[5]); w.w = cvt_pk_bf16(hv[6], hv[7]);
;                     *(u32x4*)(H + (size_t)row * ldh + f0) = w; }
	s_nop 1
	v_cndmask_b32_e64 v40, v40, v80, s[100:101]
	v_cndmask_b32_e64 v40, v40, v83, s[98:99]
	v_cndmask_b32_e64 v39, v39, v80, s[98:99]
	ds_bpermute_b32 v35, v204, v32
	ds_bpermute_b32 v32, v203, v32
	ds_bpermute_b32 v43, v200, v33
	ds_bpermute_b32 v47, v201, v33
	v_cmp_lt_i32_e32 vcc, 0, v188
	v_cmp_eq_u32_e64 s[98:99], 0, v188
	v_cmp_eq_u32_e64 s[100:101], 1, v188
	s_waitcnt lgkmcnt(0)
	s_nop 1
	v_cndmask_b32_e64 v47, v47, v81, s[100:101]
	v_cndmask_b32_e64 v47, v47, v84, s[98:99]
	v_cndmask_b32_e64 v43, v43, v81, s[98:99]
	ds_bpermute_b32 v36, v204, v33
	ds_bpermute_b32 v33, v203, v33
	ds_bpermute_b32 v66, v200, v34
	ds_bpermute_b32 v67, v201, v34
	v_cmp_lt_i32_e32 vcc, 0, v188
	v_cmp_eq_u32_e64 s[98:99], 0, v188
	v_cmp_eq_u32_e64 s[100:101], 1, v188
	s_waitcnt lgkmcnt(0)
	s_nop 1
	v_cndmask_b32_e64 v67, v67, v82, s[100:101]
	v_cndmask_b32_e64 v67, v67, v85, s[98:99]
	v_cndmask_b32_e64 v66, v66, v82, s[98:99]
	ds_bpermute_b32 v37, v204, v34
	ds_bpermute_b32 v34, v203, v34
	ds_bpermute_b32 v64, v200, v38
	ds_bpermute_b32 v65, v201, v38
	v_cmp_lt_i32_e32 vcc, 0, v188
	v_cmp_eq_u32_e64 s[98:99], 0, v188
	v_cmp_eq_u32_e64 s[100:101], 1, v188
	s_waitcnt lgkmcnt(0)
	s_nop 1
	v_cndmask_b32_e64 v65, v65, v42, s[100:101]
	v_cndmask_b32_e64 v65, v65, v41, s[98:99]
	v_cndmask_b32_e64 v64, v64, v42, s[98:99]
	s_waitcnt lgkmcnt(4)
	v_lshlrev_b32_e32 v41, 16, v67
	v_fma_f32 v41, v56, v41, v52
	v_lshlrev_b32_e32 v42, 16, v66
	v_fmac_f32_e32 v41, v48, v42
	v_fmac_f32_e32 v41, v20, v44
	v_and_b32_e32 v20, 0xffff0000, v67
	v_fma_f32 v20, v57, v20, v53
	v_and_b32_e32 v42, 0xffff0000, v66
	v_fmac_f32_e32 v20, v49, v42
	v_fmac_f32_e32 v20, v21, v45
	v_mul_f32_e32 v21, 0x3d372713, v41
	v_mul_f32_e32 v21, v41, v21
	v_mul_f32_e32 v42, 0x3d372713, v20
	v_fma_f32 v21, v41, v21, v41
	v_mul_f32_e32 v42, v20, v42
	v_mul_f32_e32 v21, 0xc0135761, v21
	v_fma_f32 v42, v20, v42, v20
	v_exp_f32_e32 v21, v21
	v_mul_f32_e32 v42, 0xc0135761, v42
	v_exp_f32_e32 v42, v42
	s_waitcnt lgkmcnt(1)
	v_and_b32_e32 v145, 0xffff0000, v64
	v_add_f32_e32 v21, 1.0, v21
	v_rcp_f32_e32 v21, v21
	v_add_f32_e32 v42, 1.0, v42
	v_rcp_f32_e32 v42, v42
	v_cmp_lt_i32_e32 vcc, 0, v188
	v_mul_f32_e32 v21, v41, v21
	v_mul_f32_e32 v41, v16, v21
	v_mul_f32_e32 v16, v20, v42
	v_lshlrev_b32_e32 v20, 16, v47
	v_fma_f32 v20, v78, v20, v62
	v_lshlrev_b32_e32 v21, 16, v43
	v_fmac_f32_e32 v20, v70, v21
	v_fmac_f32_e32 v20, v30, v74
	v_mul_f32_e32 v30, 0x3d372713, v20
	v_mul_f32_e32 v30, v20, v30
	v_fma_f32 v30, v20, v30, v20
	v_mul_f32_e32 v30, 0xc0135761, v30
	v_exp_f32_e32 v30, v30
	v_and_b32_e32 v21, 0xffff0000, v47
	v_fma_f32 v21, v79, v21, v63
	v_and_b32_e32 v42, 0xffff0000, v43
	v_add_f32_e32 v30, 1.0, v30
	v_rcp_f32_e32 v30, v30
	v_fmac_f32_e32 v21, v71, v42
	v_fmac_f32_e32 v21, v31, v75
	v_mul_f32_e32 v31, 0x3d372713, v21
	v_mul_f32_e32 v42, v17, v16
	v_lshlrev_b32_e32 v17, 16, v40
	v_mul_f32_e32 v31, v21, v31
	v_mul_f32_e32 v16, v20, v30
	v_fma_f32 v17, v76, v17, v60
	v_lshlrev_b32_e32 v20, 16, v39
	v_fma_f32 v31, v21, v31, v21
	v_fmac_f32_e32 v17, v68, v20
	v_and_b32_e32 v20, 0xffff0000, v40
	v_mul_f32_e32 v31, 0xc0135761, v31
	v_fmac_f32_e32 v17, v28, v72
	v_fma_f32 v20, v77, v20, v61
	v_and_b32_e32 v28, 0xffff0000, v39
	v_exp_f32_e32 v31, v31
	v_fmac_f32_e32 v20, v69, v28
	v_fmac_f32_e32 v20, v29, v73
	v_mul_f32_e32 v28, 0x3d372713, v17
	v_mul_f32_e32 v28, v17, v28
	v_mul_f32_e32 v29, 0x3d372713, v20
	v_fma_f32 v28, v17, v28, v17
	v_mul_f32_e32 v29, v20, v29
	v_mul_f32_e32 v26, v26, v16
	v_add_f32_e32 v16, 1.0, v31
	v_mul_f32_e32 v28, 0xc0135761, v28
	v_fma_f32 v29, v20, v29, v20
	v_rcp_f32_e32 v16, v16
	v_exp_f32_e32 v28, v28
	v_mul_f32_e32 v29, 0xc0135761, v29
	v_exp_f32_e32 v29, v29
	v_mul_f32_e32 v16, v21, v16
	v_add_f32_e32 v21, 1.0, v28
	v_rcp_f32_e32 v21, v21
	v_add_f32_e32 v28, 1.0, v29
	v_rcp_f32_e32 v28, v28
	v_mul_f32_e32 v27, v27, v16
	v_mul_f32_e32 v16, v17, v21
	v_mul_f32_e32 v24, v24, v16
	v_mul_f32_e32 v16, v20, v28
	v_mul_f32_e32 v25, v25, v16
	s_waitcnt lgkmcnt(0)
	v_and_b32_e32 v16, 0xffff0000, v65
	v_fma_f32 v21, v59, v16, v55
	v_mov_b32_e32 v16, v23
	v_mov_b32_e32 v17, v51
	v_pk_mul_f32 v[16:17], v[16:17], v[144:145]
	v_lshlrev_b32_e32 v47, 16, v64
	v_add_f32_e32 v17, v21, v17
	v_add_f32_e32 v28, v16, v17
	v_mul_f32_e32 v16, 0x3d372713, v28
	v_mul_f32_e32 v16, v28, v16
	v_fma_f32 v16, v28, v16, v28
	v_mul_f32_e32 v16, 0xc0135761, v16
	v_exp_f32_e32 v29, v16
	v_lshlrev_b32_e32 v16, 16, v65
	v_mov_b32_e32 v23, v50
	v_fma_f32 v21, v58, v16, v54
	v_pk_mul_f32 v[16:17], v[22:23], v[46:47]
	v_add_f32_e32 v22, 1.0, v29
	v_add_f32_e32 v17, v21, v17
	v_add_f32_e32 v16, v16, v17
	v_mul_f32_e32 v17, 0x3d372713, v16
	v_mul_f32_e32 v17, v16, v17
	v_fma_f32 v17, v16, v17, v16
	v_mul_f32_e32 v17, 0xc0135761, v17
	v_exp_f32_e32 v17, v17
	v_rcp_f32_e32 v22, v22
	v_add_u32_e32 v29, 0xa0, v202
	ds_bpermute_b32 v20, v204, v38
	v_add_f32_e32 v17, 1.0, v17
	v_rcp_f32_e32 v17, v17
	v_mul_f32_e32 v22, v28, v22
	v_mul_f32_e32 v19, v19, v22
	ds_bpermute_b32 v21, v203, v38
	v_mul_f32_e32 v16, v16, v17
	v_mul_f32_e32 v22, v18, v16
	v_cvt_pk_bf16_f32 v16, v24, v25
	v_cvt_pk_bf16_f32 v17, v26, v27
	v_cvt_pk_bf16_f32 v18, v41, v42
	v_cvt_pk_bf16_f32 v19, v22, v19
	v_mov_b64_e32 v[22:23], s[14:15]
	v_mad_i64_i32 v[22:23], s[62:63], v29, s91, v[22:23]
	v_lshl_add_u64 v[22:23], v[180:181], 1, v[22:23]
	global_store_dwordx4 v[22:23], v[16:19], off
	s_nop 1
	v_cvt_pk_bf16_f32 v17, v12, v13
	ds_bpermute_b32 v16, v200, v17
	ds_bpermute_b32 v17, v201, v17
	v_cvt_pk_bf16_f32 v19, v14, v15
	v_cvt_pk_bf16_f32 v22, v4, v5
	v_cvt_pk_bf16_f32 v23, v6, v7
	v_cmp_eq_u32_e64 s[98:99], 0, v188
	v_cmp_eq_u32_e64 s[100:101], 1, v188
	s_waitcnt lgkmcnt(0)
; __device__ __forceinline__ unsigned cvt_pk_bf16(float lo, float hi) { unsigned r; asm volatile("v_cvt_pk_bf16_f32 %0, %1, %2" : "=v"(r) : "v"(lo), "v"(hi)); return r; }
; __device__ __forceinline__ float gelu_tanh_f(float x) { const float y = -2.3022081983651455f * (x + 0.044715f * x * x * x); return x * __builtin_amdgcn_rcpf(1.f + __builtin_amdgcn_exp2f(y)); }
;     __device__ __forceinline__ void operator()(const f32x4 (&acc)[2][2][4][2], const Unit& u, int wr, int wc, int fr, int fq) const {
;     ...
;                 for (int q = 0; q < 4; ++q) {
;                     unsigned g1 = (unsigned)__shfl_up((int)pk[q], 1, 16), g2 = (unsigned)__shfl_up((int)pk[q], 2, 16);
;                     if (fr == 0) { g1 = l15[q]; g2 = l14[q]; } else if (fr == 1) { g2 = l15[q]; }
;                     const unsigned n14 = (unsigned)__shfl((int)pk[q], 14, 16), n15 = (unsigned)__shfl((int)pk[q], 15, 16);
;                     l14[q] = n14; l15[q] = n15;
;                     const int n = q >> 1, j = (q & 1) * 2, e = 2 * q;
;                     const float x0 = bb[e] + w0[e] * __uint_as_float(g2 << 16) + w1[e] * __uint_as_float(g1 << 16) + w2[e] * acc[ai][0][m][n][j];
;                     const float x1 = bb[e + 1] + w0[e + 1] * __uint_as_float(g2 & 0xffff0000u) + w1[e + 1] * __uint_as_float(g1 & 0xffff0000u) + w2[e + 1] * acc[ai][0][m][n][j + 1];
;                     hv[e] = gelu_tanh_f(x0) * acc[ai][1][m][n][j]; hv[e + 1] = gelu_tanh_f(x1) * acc[ai][1][m][n][j + 1];
;                 }
;                 const bool first2 = (slab == 0 && m == 0 && fr < 2);
;                 if (!first2) { u32x4 w; w.x = cvt_pk_bf16(hv[0], hv[1]); w.y = cvt_pk_bf16(hv[2], hv[3]); w.z = cvt_pk_bf16(hv[4], hv[5]); w.w = cvt_pk_bf16(hv[6], hv[7]);
;                     *(u32x4*)(H + (size_t)row * ldh + f0) = w; }
;                 else { float* p = hp + (size_t)fr * ff; *(f32x4*)p = acc[0][0][0][0]; *(f32x4*)(p + 4) = acc[0][0][0][1];
;                     float* pu = hp + (size_t)(4 + fr) * ff; *(f32x4*)pu = acc[0][1][0][0]; *(f32x4*)(pu + 4) = acc[0][1][0][1]; }
;                 if (slab == 3 && m == 3 && fr >= 14) { float* p = hp + (size_t)(2 + fr - 14) * ff; *(f32x4*)p = acc[1][0][3][0]; *(f32x4*)(p + 4) = acc[1][0][3][1]; }
	s_nop 1
	v_cndmask_b32_e64 v17, v17, v32, s[100:101]
	v_cndmask_b32_e64 v17, v17, v35, s[98:99]
	v_cndmask_b32_e64 v16, v16, v32, s[98:99]
	ds_bpermute_b32 v18, v200, v19
	ds_bpermute_b32 v19, v201, v19
	v_cmp_lt_i32_e32 vcc, 0, v188
	v_cmp_eq_u32_e64 s[98:99], 0, v188
	v_cmp_eq_u32_e64 s[100:101], 1, v188
	s_waitcnt lgkmcnt(0)
	s_nop 1
	v_cndmask_b32_e64 v19, v19, v33, s[100:101]
	v_cndmask_b32_e64 v19, v19, v36, s[98:99]
	v_cndmask_b32_e64 v18, v18, v33, s[98:99]
	ds_bpermute_b32 v24, v200, v22
	ds_bpermute_b32 v25, v201, v22
	v_cmp_lt_i32_e32 vcc, 0, v188
	v_cmp_eq_u32_e64 s[98:99], 0, v188
	v_cmp_eq_u32_e64 s[100:101], 1, v188
	s_waitcnt lgkmcnt(0)
	s_nop 1
	v_cndmask_b32_e64 v25, v25, v34, s[100:101]
	v_cndmask_b32_e64 v25, v25, v37, s[98:99]
	v_cndmask_b32_e64 v24, v24, v34, s[98:99]
	ds_bpermute_b32 v22, v200, v23
	ds_bpermute_b32 v23, v201, v23
	v_cmp_lt_i32_e32 vcc, 0, v188
	v_cmp_eq_u32_e64 s[98:99], 0, v188
	v_cmp_eq_u32_e64 s[100:101], 1, v188
	s_waitcnt lgkmcnt(0)
	s_nop 1
	v_cndmask_b32_e64 v23, v23, v21, s[100:101]
	v_cndmask_b32_e64 v23, v23, v20, s[98:99]
	v_cndmask_b32_e64 v22, v22, v21, s[98:99]
	s_waitcnt lgkmcnt(2)
	v_lshlrev_b32_e32 v20, 16, v25
	v_fma_f32 v20, v56, v20, v52
	v_lshlrev_b32_e32 v21, 16, v24
	v_fmac_f32_e32 v20, v48, v21
	v_and_b32_e32 v21, 0xffff0000, v25
	v_fma_f32 v21, v57, v21, v53
	v_and_b32_e32 v24, 0xffff0000, v24
	v_fmac_f32_e32 v20, v4, v44
	v_fmac_f32_e32 v21, v49, v24
	v_fmac_f32_e32 v21, v5, v45
	v_mul_f32_e32 v24, 0x3d372713, v20
	v_mul_f32_e32 v24, v20, v24
	v_mul_f32_e32 v25, 0x3d372713, v21
	v_fma_f32 v24, v20, v24, v20
	v_mul_f32_e32 v25, v21, v25
	v_mul_f32_e32 v24, 0xc0135761, v24
	v_fma_f32 v25, v21, v25, v21
	v_exp_f32_e32 v24, v24
	v_mul_f32_e32 v25, 0xc0135761, v25
	v_exp_f32_e32 v25, v25
	s_waitcnt lgkmcnt(1)
	v_and_b32_e32 v145, 0xffff0000, v22
	v_add_f32_e32 v24, 1.0, v24
	v_rcp_f32_e32 v24, v24
	v_add_f32_e32 v25, 1.0, v25
	v_rcp_f32_e32 v25, v25
	v_lshlrev_b32_e32 v47, 16, v22
	v_mul_f32_e32 v20, v20, v24
	v_mul_f32_e32 v20, v0, v20
	v_mul_f32_e32 v0, v21, v25
	v_lshlrev_b32_e32 v21, 16, v19
	v_fma_f32 v21, v78, v21, v62
	v_lshlrev_b32_e32 v24, 16, v18
	v_fmac_f32_e32 v21, v70, v24
	v_fmac_f32_e32 v21, v14, v74
	v_mul_f32_e32 v24, 0x3d372713, v21
	v_mul_f32_e32 v24, v21, v24
	v_fma_f32 v24, v21, v24, v21
	v_mul_f32_e32 v24, 0xc0135761, v24
	v_exp_f32_e32 v24, v24
	v_and_b32_e32 v19, 0xffff0000, v19
	v_fma_f32 v19, v79, v19, v63
	v_and_b32_e32 v18, 0xffff0000, v18
	v_fmac_f32_e32 v19, v71, v18
	v_add_f32_e32 v18, 1.0, v24
	v_rcp_f32_e32 v18, v18
	v_mul_f32_e32 v25, v1, v0
	v_lshlrev_b32_e32 v1, 16, v17
	v_fma_f32 v1, v76, v1, v60
	v_mul_f32_e32 v0, v21, v18
	v_lshlrev_b32_e32 v18, 16, v16
	v_fmac_f32_e32 v19, v15, v75
	v_fmac_f32_e32 v1, v68, v18
	v_and_b32_e32 v17, 0xffff0000, v17
	v_mul_f32_e32 v24, 0x3d372713, v19
	v_fmac_f32_e32 v1, v12, v72
	v_fmac_f32_e32 v61, v77, v17
	v_and_b32_e32 v16, 0xffff0000, v16
	v_mul_f32_e32 v24, v19, v24
	v_fmac_f32_e32 v61, v69, v16
	v_mul_f32_e32 v16, 0x3d372713, v1
	v_fma_f32 v24, v19, v24, v19
	v_fmac_f32_e32 v61, v13, v73
	v_mul_f32_e32 v16, v1, v16
	v_mul_f32_e32 v24, 0xc0135761, v24
	v_fma_f32 v16, v1, v16, v1
	v_mul_f32_e32 v17, 0x3d372713, v61
	v_exp_f32_e32 v24, v24
	v_mul_f32_e32 v16, 0xc0135761, v16
	v_mul_f32_e32 v17, v61, v17
	v_exp_f32_e32 v16, v16
	v_fma_f32 v17, v61, v17, v61
	v_mul_f32_e32 v17, 0xc0135761, v17
	v_exp_f32_e32 v17, v17
	v_mul_f32_e32 v10, v10, v0
	v_add_f32_e32 v0, 1.0, v24
	v_rcp_f32_e32 v0, v0
	v_add_f32_e32 v16, 1.0, v16
	v_rcp_f32_e32 v16, v16
	v_add_f32_e32 v17, 1.0, v17
	v_rcp_f32_e32 v17, v17
	v_mul_f32_e32 v0, v19, v0
	v_mul_f32_e32 v11, v11, v0
	v_mul_f32_e32 v0, v1, v16
	v_mul_f32_e32 v8, v8, v0
	s_waitcnt lgkmcnt(0)
	v_and_b32_e32 v0, 0xffff0000, v23
	v_mul_f32_e32 v16, v61, v17
	v_fma_f32 v17, v59, v0, v55
	v_mov_b32_e32 v0, v7
	v_mov_b32_e32 v1, v51
	v_pk_mul_f32 v[0:1], v[0:1], v[144:145]
	v_mul_f32_e32 v9, v9, v16
	v_add_f32_e32 v1, v17, v1
	v_add_f32_e32 v17, v0, v1
	v_mul_f32_e32 v0, 0x3d372713, v17
	v_mul_f32_e32 v0, v17, v0
	v_fma_f32 v0, v17, v0, v17
	v_mul_f32_e32 v0, 0xc0135761, v0
	v_exp_f32_e32 v18, v0
	v_lshlrev_b32_e32 v0, 16, v23
	v_fmac_f32_e32 v54, v58, v0
	v_mov_b32_e32 v0, v6
	v_mov_b32_e32 v1, v50
	v_pk_mul_f32 v[0:1], v[0:1], v[46:47]
	v_add_f32_e32 v16, 1.0, v18
	v_add_f32_e32 v1, v54, v1
	v_add_f32_e32 v0, v0, v1
	v_mul_f32_e32 v1, 0x3d372713, v0
	v_mul_f32_e32 v1, v0, v1
	v_fma_f32 v1, v0, v1, v0
	v_mul_f32_e32 v1, 0xc0135761, v1
	v_exp_f32_e32 v1, v1
	v_rcp_f32_e32 v16, v16
	v_add_u32_e32 v18, 0xb0, v202
	v_add_f32_e32 v1, 1.0, v1
	v_rcp_f32_e32 v1, v1
	v_mul_f32_e32 v16, v17, v16
	v_mul_f32_e32 v3, v3, v16
	v_mul_f32_e32 v0, v0, v1
	v_mul_f32_e32 v16, v2, v0
	v_cvt_pk_bf16_f32 v0, v8, v9
	v_mov_b64_e32 v[8:9], s[14:15]
	v_mad_i64_i32 v[8:9], s[62:63], v18, s91, v[8:9]
	v_lshl_add_u64 v[8:9], v[180:181], 1, v[8:9]
	v_cvt_pk_bf16_f32 v1, v10, v11
	v_cvt_pk_bf16_f32 v2, v20, v25
	v_cvt_pk_bf16_f32 v3, v16, v3
	global_store_dwordx4 v[8:9], v[0:3], off
	s_and_saveexec_b64 s[62:63], s[48:49]
	s_cbranch_execz .LBB0_2613
	global_store_dwordx4 v[112:113], v[12:15], off
	global_store_dwordx4 v[112:113], v[4:7], off offset:16
